# up_ffn epilogue also stores full rows: packed bf16 pairs kept in dead accumulators, transposed through LDS after the g reads finish
# baseline (speedup 1.0000x reference)
.Lepiup_noextra:
	v_lshrrev_b32_e32 v132, 1, v129
	v_lshl_add_u32 v132, v130, 2, v132
	v_and_b32_e32 v133, 1, v129
	v_lshlrev_b32_e32 v133, 3, v133
	v_lshl_add_u32 v134, v131, 6, v128
	v_add_u32_e32 v135, 15, v128
	v_and_b32_e32 v135, 15, v135
	v_add_u32_e32 v137, 1, v128
	v_and_b32_e32 v137, 15, v137
	v_cmp_eq_u32_e64 s[38:39], 0, v134
	s_movk_i32 s1, 0x4f
	v_cmp_eq_u32_e64 s[40:41], s1, v134
	v_mov_b32_e32 v244, v132
	v_xor_b32_e32 v245, v244, v135
	v_xor_b32_e32 v246, v244, v128
	v_xor_b32_e32 v247, v244, v137
	v_lshl_add_u32 v245, v245, 4, v133
	v_lshl_add_u32 v246, v246, 4, v133
	v_lshl_add_u32 v247, v247, 4, v133
	v_lshlrev_b32_e32 v248, 9, v134
	v_add_u32_e32 v194, v248, v246
	v_add_u32_e32 v249, 0x200, v248
	v_add_u32_e32 v196, v249, v247
	v_add_u32_e32 v249, 0x1e00, v248
	v_add_u32_e32 v190, v249, v245
	v_add_u32_e32 v249, 0xfe00, v248
	v_add_u32_e32 v198, v249, v245
	v_add_u32_e32 v200, 0x10000, v194
	v_add_u32_e32 v202, 0x10000, v196
	v_subrev_u32_e32 v249, 0x200, v248
	v_add_u32_e32 v249, v249, v245
	v_add_u32_e32 v250, 0x20100, v245
	v_cndmask_b32_e64 v192, v249, v250, s[38:39]
	v_add_u32_e32 v249, 0x16200, v248
	v_add_u32_e32 v249, v249, v247
	v_add_u32_e32 v250, 0x20300, v247
	v_cndmask_b32_e64 v204, v249, v250, s[40:41]
	v_add_u32_e32 v244, 2, v132
	v_xor_b32_e32 v245, v244, v135
	v_xor_b32_e32 v246, v244, v128
	v_xor_b32_e32 v247, v244, v137
	v_lshl_add_u32 v245, v245, 4, v133
	v_lshl_add_u32 v246, v246, 4, v133
	v_lshl_add_u32 v247, v247, 4, v133
	v_lshlrev_b32_e32 v248, 9, v134
	v_add_u32_e32 v195, v248, v246
	v_add_u32_e32 v249, 0x200, v248
	v_add_u32_e32 v197, v249, v247
	v_add_u32_e32 v249, 0x1e00, v248
	v_add_u32_e32 v191, v249, v245
	v_add_u32_e32 v249, 0xfe00, v248
	v_add_u32_e32 v199, v249, v245
	v_add_u32_e32 v201, 0x10000, v195
	v_add_u32_e32 v203, 0x10000, v197
	v_subrev_u32_e32 v249, 0x200, v248
	v_add_u32_e32 v249, v249, v245
	v_add_u32_e32 v250, 0x20100, v245
	v_cndmask_b32_e64 v193, v249, v250, s[38:39]
	v_add_u32_e32 v249, 0x16200, v248
	v_add_u32_e32 v249, v249, v247
	v_add_u32_e32 v250, 0x20300, v247
	v_cndmask_b32_e64 v205, v249, v250, s[40:41]
	s_waitcnt vmcnt(0) lgkmcnt(0)
	s_barrier
	ds_read_b64 v[232:233], v192
	ds_read_b64 v[234:235], v194
	ds_read_b64 v[236:237], v196
	ds_read_b64 v[238:239], v193
	ds_read_b64 v[240:241], v195
	ds_read_b64 v[242:243], v197
	s_waitcnt lgkmcnt(3)
	v_lshlrev_b32_e32 v244, 16, v232
	v_and_b32_e32 v245, 0xffff0000, v232
	v_lshlrev_b32_e32 v246, 16, v233
	v_and_b32_e32 v247, 0xffff0000, v233
	v_mul_f32_e32 v248, v142, v244
	v_mul_f32_e32 v249, v143, v245
	v_mul_f32_e32 v250, v144, v246
	v_mul_f32_e32 v251, v145, v247
	v_lshlrev_b32_e32 v244, 16, v234
	v_and_b32_e32 v245, 0xffff0000, v234
	v_lshlrev_b32_e32 v246, 16, v235
	v_and_b32_e32 v247, 0xffff0000, v235
	v_fmac_f32_e32 v248, v146, v244
	v_fmac_f32_e32 v249, v147, v245
	v_fmac_f32_e32 v250, v148, v246
	v_fmac_f32_e32 v251, v149, v247
	v_lshlrev_b32_e32 v244, 16, v236
	v_and_b32_e32 v245, 0xffff0000, v236
	v_lshlrev_b32_e32 v246, 16, v237
	v_and_b32_e32 v247, 0xffff0000, v237
	v_fmac_f32_e32 v248, v150, v244
	v_fmac_f32_e32 v249, v151, v245
	v_fmac_f32_e32 v250, v152, v246
	v_fmac_f32_e32 v251, v153, v247
	v_mul_f32_e32 v244, 0xbfb8aa3b, v248
	v_mul_f32_e32 v245, 0xbfb8aa3b, v249
	v_mul_f32_e32 v246, 0xbfb8aa3b, v250
	v_mul_f32_e32 v247, 0xbfb8aa3b, v251
	v_exp_f32_e32 v244, v244
	v_exp_f32_e32 v245, v245
	v_exp_f32_e32 v246, v246
	v_exp_f32_e32 v247, v247
	v_add_f32_e32 v244, 1.0, v244
	v_add_f32_e32 v245, 1.0, v245
	v_add_f32_e32 v246, 1.0, v246
	v_add_f32_e32 v247, 1.0, v247
	v_rcp_f32_e32 v244, v244
	v_rcp_f32_e32 v245, v245
	v_rcp_f32_e32 v246, v246
	v_rcp_f32_e32 v247, v247
	v_mul_f32_e32 v248, v248, v244
	v_mul_f32_e32 v249, v249, v245
	v_mul_f32_e32 v250, v250, v246
	v_mul_f32_e32 v251, v251, v247
	v_mul_f32_e32 v138, v138, v248
	v_mul_f32_e32 v139, v139, v249
	v_mul_f32_e32 v140, v140, v250
	v_mul_f32_e32 v141, v141, v251
	v_cvt_pk_bf16_f32 v138, v138, v139
	v_cvt_pk_bf16_f32 v139, v140, v141
	ds_read_b64 v[232:233], v192 offset:256
	ds_read_b64 v[234:235], v194 offset:256
	ds_read_b64 v[236:237], v196 offset:256
	s_waitcnt lgkmcnt(3)
	v_lshlrev_b32_e32 v244, 16, v238
	v_and_b32_e32 v245, 0xffff0000, v238
	v_lshlrev_b32_e32 v246, 16, v239
	v_and_b32_e32 v247, 0xffff0000, v239
	v_mul_f32_e32 v248, v154, v244
	v_mul_f32_e32 v249, v155, v245
	v_mul_f32_e32 v250, v156, v246
	v_mul_f32_e32 v251, v157, v247
	v_lshlrev_b32_e32 v244, 16, v240
	v_and_b32_e32 v245, 0xffff0000, v240
	v_lshlrev_b32_e32 v246, 16, v241
	v_and_b32_e32 v247, 0xffff0000, v241
	v_fmac_f32_e32 v248, v158, v244
	v_fmac_f32_e32 v249, v159, v245
	v_fmac_f32_e32 v250, v160, v246
	v_fmac_f32_e32 v251, v161, v247
	v_lshlrev_b32_e32 v244, 16, v242
	v_and_b32_e32 v245, 0xffff0000, v242
	v_lshlrev_b32_e32 v246, 16, v243
	v_and_b32_e32 v247, 0xffff0000, v243
	v_fmac_f32_e32 v248, v162, v244
	v_fmac_f32_e32 v249, v163, v245
	v_fmac_f32_e32 v250, v164, v246
	v_fmac_f32_e32 v251, v165, v247
	v_mul_f32_e32 v244, 0xbfb8aa3b, v248
	v_mul_f32_e32 v245, 0xbfb8aa3b, v249
	v_mul_f32_e32 v246, 0xbfb8aa3b, v250
	v_mul_f32_e32 v247, 0xbfb8aa3b, v251
	v_exp_f32_e32 v244, v244
	v_exp_f32_e32 v245, v245
	v_exp_f32_e32 v246, v246
	v_exp_f32_e32 v247, v247
	v_add_f32_e32 v244, 1.0, v244
	v_add_f32_e32 v245, 1.0, v245
	v_add_f32_e32 v246, 1.0, v246
	v_add_f32_e32 v247, 1.0, v247
	v_rcp_f32_e32 v244, v244
	v_rcp_f32_e32 v245, v245
	v_rcp_f32_e32 v246, v246
	v_rcp_f32_e32 v247, v247
	v_mul_f32_e32 v248, v248, v244
	v_mul_f32_e32 v249, v249, v245
	v_mul_f32_e32 v250, v250, v246
	v_mul_f32_e32 v251, v251, v247
	v_mul_f32_e32 v122, v122, v248
	v_mul_f32_e32 v123, v123, v249
	v_mul_f32_e32 v124, v124, v250
	v_mul_f32_e32 v125, v125, v251
	v_cvt_pk_bf16_f32 v122, v122, v123
	v_cvt_pk_bf16_f32 v123, v124, v125
	ds_read_b64 v[238:239], v193 offset:256
	ds_read_b64 v[240:241], v195 offset:256
	ds_read_b64 v[242:243], v197 offset:256
	s_waitcnt lgkmcnt(3)
	v_lshlrev_b32_e32 v244, 16, v232
	v_and_b32_e32 v245, 0xffff0000, v232
	v_lshlrev_b32_e32 v246, 16, v233
	v_and_b32_e32 v247, 0xffff0000, v233
	v_mul_f32_e32 v248, v166, v244
	v_mul_f32_e32 v249, v167, v245
	v_mul_f32_e32 v250, v168, v246
	v_mul_f32_e32 v251, v169, v247
	v_lshlrev_b32_e32 v244, 16, v234
	v_and_b32_e32 v245, 0xffff0000, v234
	v_lshlrev_b32_e32 v246, 16, v235
	v_and_b32_e32 v247, 0xffff0000, v235
	v_fmac_f32_e32 v248, v170, v244
	v_fmac_f32_e32 v249, v171, v245
	v_fmac_f32_e32 v250, v172, v246
	v_fmac_f32_e32 v251, v173, v247
	v_lshlrev_b32_e32 v244, 16, v236
	v_and_b32_e32 v245, 0xffff0000, v236
	v_lshlrev_b32_e32 v246, 16, v237
	v_and_b32_e32 v247, 0xffff0000, v237
	v_fmac_f32_e32 v248, v174, v244
	v_fmac_f32_e32 v249, v175, v245
	v_fmac_f32_e32 v250, v176, v246
	v_fmac_f32_e32 v251, v177, v247
	v_mul_f32_e32 v244, 0xbfb8aa3b, v248
	v_mul_f32_e32 v245, 0xbfb8aa3b, v249
	v_mul_f32_e32 v246, 0xbfb8aa3b, v250
	v_mul_f32_e32 v247, 0xbfb8aa3b, v251
	v_exp_f32_e32 v244, v244
	v_exp_f32_e32 v245, v245
	v_exp_f32_e32 v246, v246
	v_exp_f32_e32 v247, v247
	v_add_f32_e32 v244, 1.0, v244
	v_add_f32_e32 v245, 1.0, v245
	v_add_f32_e32 v246, 1.0, v246
	v_add_f32_e32 v247, 1.0, v247
	v_rcp_f32_e32 v244, v244
	v_rcp_f32_e32 v245, v245
	v_rcp_f32_e32 v246, v246
	v_rcp_f32_e32 v247, v247
	v_mul_f32_e32 v248, v248, v244
	v_mul_f32_e32 v249, v249, v245
	v_mul_f32_e32 v250, v250, v246
	v_mul_f32_e32 v251, v251, v247
	v_mul_f32_e32 v118, v118, v248
	v_mul_f32_e32 v119, v119, v249
	v_mul_f32_e32 v120, v120, v250
	v_mul_f32_e32 v121, v121, v251
	v_cvt_pk_bf16_f32 v118, v118, v119
	v_cvt_pk_bf16_f32 v119, v120, v121
	ds_read_b64 v[232:233], v190
	ds_read_b64 v[234:235], v194 offset:8192
	ds_read_b64 v[236:237], v196 offset:8192
	s_waitcnt lgkmcnt(3)
	v_lshlrev_b32_e32 v244, 16, v238
	v_and_b32_e32 v245, 0xffff0000, v238
	v_lshlrev_b32_e32 v246, 16, v239
	v_and_b32_e32 v247, 0xffff0000, v239
	v_mul_f32_e32 v248, v178, v244
	v_mul_f32_e32 v249, v179, v245
	v_mul_f32_e32 v250, v180, v246
	v_mul_f32_e32 v251, v181, v247
	v_lshlrev_b32_e32 v244, 16, v240
	v_and_b32_e32 v245, 0xffff0000, v240
	v_lshlrev_b32_e32 v246, 16, v241
	v_and_b32_e32 v247, 0xffff0000, v241
	v_fmac_f32_e32 v248, v182, v244
	v_fmac_f32_e32 v249, v183, v245
	v_fmac_f32_e32 v250, v184, v246
	v_fmac_f32_e32 v251, v185, v247
	v_lshlrev_b32_e32 v244, 16, v242
	v_and_b32_e32 v245, 0xffff0000, v242
	v_lshlrev_b32_e32 v246, 16, v243
	v_and_b32_e32 v247, 0xffff0000, v243
	v_fmac_f32_e32 v248, v186, v244
	v_fmac_f32_e32 v249, v187, v245
	v_fmac_f32_e32 v250, v188, v246
	v_fmac_f32_e32 v251, v189, v247
	v_mul_f32_e32 v244, 0xbfb8aa3b, v248
	v_mul_f32_e32 v245, 0xbfb8aa3b, v249
	v_mul_f32_e32 v246, 0xbfb8aa3b, v250
	v_mul_f32_e32 v247, 0xbfb8aa3b, v251
	v_exp_f32_e32 v244, v244
	v_exp_f32_e32 v245, v245
	v_exp_f32_e32 v246, v246
	v_exp_f32_e32 v247, v247
	v_add_f32_e32 v244, 1.0, v244
	v_add_f32_e32 v245, 1.0, v245
	v_add_f32_e32 v246, 1.0, v246
	v_add_f32_e32 v247, 1.0, v247
	v_rcp_f32_e32 v244, v244
	v_rcp_f32_e32 v245, v245
	v_rcp_f32_e32 v246, v246
	v_rcp_f32_e32 v247, v247
	v_mul_f32_e32 v248, v248, v244
	v_mul_f32_e32 v249, v249, v245
	v_mul_f32_e32 v250, v250, v246
	v_mul_f32_e32 v251, v251, v247
	v_mul_f32_e32 v114, v114, v248
	v_mul_f32_e32 v115, v115, v249
	v_mul_f32_e32 v116, v116, v250
	v_mul_f32_e32 v117, v117, v251
	v_cvt_pk_bf16_f32 v114, v114, v115
	v_cvt_pk_bf16_f32 v115, v116, v117
	ds_read_b64 v[238:239], v191
	ds_read_b64 v[240:241], v195 offset:8192
	ds_read_b64 v[242:243], v197 offset:8192
	s_waitcnt lgkmcnt(3)
	v_lshlrev_b32_e32 v244, 16, v232
	v_and_b32_e32 v245, 0xffff0000, v232
	v_lshlrev_b32_e32 v246, 16, v233
	v_and_b32_e32 v247, 0xffff0000, v233
	v_mul_f32_e32 v248, v142, v244
	v_mul_f32_e32 v249, v143, v245
	v_mul_f32_e32 v250, v144, v246
	v_mul_f32_e32 v251, v145, v247
	v_lshlrev_b32_e32 v244, 16, v234
	v_and_b32_e32 v245, 0xffff0000, v234
	v_lshlrev_b32_e32 v246, 16, v235
	v_and_b32_e32 v247, 0xffff0000, v235
	v_fmac_f32_e32 v248, v146, v244
	v_fmac_f32_e32 v249, v147, v245
	v_fmac_f32_e32 v250, v148, v246
	v_fmac_f32_e32 v251, v149, v247
	v_lshlrev_b32_e32 v244, 16, v236
	v_and_b32_e32 v245, 0xffff0000, v236
	v_lshlrev_b32_e32 v246, 16, v237
	v_and_b32_e32 v247, 0xffff0000, v237
	v_fmac_f32_e32 v248, v150, v244
	v_fmac_f32_e32 v249, v151, v245
	v_fmac_f32_e32 v250, v152, v246
	v_fmac_f32_e32 v251, v153, v247
	v_mul_f32_e32 v244, 0xbfb8aa3b, v248
	v_mul_f32_e32 v245, 0xbfb8aa3b, v249
	v_mul_f32_e32 v246, 0xbfb8aa3b, v250
	v_mul_f32_e32 v247, 0xbfb8aa3b, v251
	v_exp_f32_e32 v244, v244
	v_exp_f32_e32 v245, v245
	v_exp_f32_e32 v246, v246
	v_exp_f32_e32 v247, v247
	v_add_f32_e32 v244, 1.0, v244
	v_add_f32_e32 v245, 1.0, v245
	v_add_f32_e32 v246, 1.0, v246
	v_add_f32_e32 v247, 1.0, v247
	v_rcp_f32_e32 v244, v244
	v_rcp_f32_e32 v245, v245
	v_rcp_f32_e32 v246, v246
	v_rcp_f32_e32 v247, v247
	v_mul_f32_e32 v248, v248, v244
	v_mul_f32_e32 v249, v249, v245
	v_mul_f32_e32 v250, v250, v246
	v_mul_f32_e32 v251, v251, v247
	v_mul_f32_e32 v110, v110, v248
	v_mul_f32_e32 v111, v111, v249
	v_mul_f32_e32 v112, v112, v250
	v_mul_f32_e32 v113, v113, v251
	v_cvt_pk_bf16_f32 v110, v110, v111
	v_cvt_pk_bf16_f32 v111, v112, v113
	ds_read_b64 v[232:233], v190 offset:256
	ds_read_b64 v[234:235], v194 offset:8448
	ds_read_b64 v[236:237], v196 offset:8448
	s_waitcnt lgkmcnt(3)
	v_lshlrev_b32_e32 v244, 16, v238
	v_and_b32_e32 v245, 0xffff0000, v238
	v_lshlrev_b32_e32 v246, 16, v239
	v_and_b32_e32 v247, 0xffff0000, v239
	v_mul_f32_e32 v248, v154, v244
	v_mul_f32_e32 v249, v155, v245
	v_mul_f32_e32 v250, v156, v246
	v_mul_f32_e32 v251, v157, v247
	v_lshlrev_b32_e32 v244, 16, v240
	v_and_b32_e32 v245, 0xffff0000, v240
	v_lshlrev_b32_e32 v246, 16, v241
	v_and_b32_e32 v247, 0xffff0000, v241
	v_fmac_f32_e32 v248, v158, v244
	v_fmac_f32_e32 v249, v159, v245
	v_fmac_f32_e32 v250, v160, v246
	v_fmac_f32_e32 v251, v161, v247
	v_lshlrev_b32_e32 v244, 16, v242
	v_and_b32_e32 v245, 0xffff0000, v242
	v_lshlrev_b32_e32 v246, 16, v243
	v_and_b32_e32 v247, 0xffff0000, v243
	v_fmac_f32_e32 v248, v162, v244
	v_fmac_f32_e32 v249, v163, v245
	v_fmac_f32_e32 v250, v164, v246
	v_fmac_f32_e32 v251, v165, v247
	v_mul_f32_e32 v244, 0xbfb8aa3b, v248
	v_mul_f32_e32 v245, 0xbfb8aa3b, v249
	v_mul_f32_e32 v246, 0xbfb8aa3b, v250
	v_mul_f32_e32 v247, 0xbfb8aa3b, v251
	v_exp_f32_e32 v244, v244
	v_exp_f32_e32 v245, v245
	v_exp_f32_e32 v246, v246
	v_exp_f32_e32 v247, v247
	v_add_f32_e32 v244, 1.0, v244
	v_add_f32_e32 v245, 1.0, v245
	v_add_f32_e32 v246, 1.0, v246
	v_add_f32_e32 v247, 1.0, v247
	v_rcp_f32_e32 v244, v244
	v_rcp_f32_e32 v245, v245
	v_rcp_f32_e32 v246, v246
	v_rcp_f32_e32 v247, v247
	v_mul_f32_e32 v248, v248, v244
	v_mul_f32_e32 v249, v249, v245
	v_mul_f32_e32 v250, v250, v246
	v_mul_f32_e32 v251, v251, v247
	v_mul_f32_e32 v106, v106, v248
	v_mul_f32_e32 v107, v107, v249
	v_mul_f32_e32 v108, v108, v250
	v_mul_f32_e32 v109, v109, v251
	v_cvt_pk_bf16_f32 v106, v106, v107
	v_cvt_pk_bf16_f32 v107, v108, v109
	ds_read_b64 v[238:239], v191 offset:256
	ds_read_b64 v[240:241], v195 offset:8448
	ds_read_b64 v[242:243], v197 offset:8448
	s_waitcnt lgkmcnt(3)
	v_lshlrev_b32_e32 v244, 16, v232
	v_and_b32_e32 v245, 0xffff0000, v232
	v_lshlrev_b32_e32 v246, 16, v233
	v_and_b32_e32 v247, 0xffff0000, v233
	v_mul_f32_e32 v248, v166, v244
	v_mul_f32_e32 v249, v167, v245
	v_mul_f32_e32 v250, v168, v246
	v_mul_f32_e32 v251, v169, v247
	v_lshlrev_b32_e32 v244, 16, v234
	v_and_b32_e32 v245, 0xffff0000, v234
	v_lshlrev_b32_e32 v246, 16, v235
	v_and_b32_e32 v247, 0xffff0000, v235
	v_fmac_f32_e32 v248, v170, v244
	v_fmac_f32_e32 v249, v171, v245
	v_fmac_f32_e32 v250, v172, v246
	v_fmac_f32_e32 v251, v173, v247
	v_lshlrev_b32_e32 v244, 16, v236
	v_and_b32_e32 v245, 0xffff0000, v236
	v_lshlrev_b32_e32 v246, 16, v237
	v_and_b32_e32 v247, 0xffff0000, v237
	v_fmac_f32_e32 v248, v174, v244
	v_fmac_f32_e32 v249, v175, v245
	v_fmac_f32_e32 v250, v176, v246
	v_fmac_f32_e32 v251, v177, v247
	v_mul_f32_e32 v244, 0xbfb8aa3b, v248
	v_mul_f32_e32 v245, 0xbfb8aa3b, v249
	v_mul_f32_e32 v246, 0xbfb8aa3b, v250
	v_mul_f32_e32 v247, 0xbfb8aa3b, v251
	v_exp_f32_e32 v244, v244
	v_exp_f32_e32 v245, v245
	v_exp_f32_e32 v246, v246
	v_exp_f32_e32 v247, v247
	v_add_f32_e32 v244, 1.0, v244
	v_add_f32_e32 v245, 1.0, v245
	v_add_f32_e32 v246, 1.0, v246
	v_add_f32_e32 v247, 1.0, v247
	v_rcp_f32_e32 v244, v244
	v_rcp_f32_e32 v245, v245
	v_rcp_f32_e32 v246, v246
	v_rcp_f32_e32 v247, v247
	v_mul_f32_e32 v248, v248, v244
	v_mul_f32_e32 v249, v249, v245
	v_mul_f32_e32 v250, v250, v246
	v_mul_f32_e32 v251, v251, v247
	v_mul_f32_e32 v102, v102, v248
	v_mul_f32_e32 v103, v103, v249
	v_mul_f32_e32 v104, v104, v250
	v_mul_f32_e32 v105, v105, v251
	v_cvt_pk_bf16_f32 v102, v102, v103
	v_cvt_pk_bf16_f32 v103, v104, v105
	ds_read_b64 v[232:233], v190 offset:8192
	ds_read_b64 v[234:235], v194 offset:16384
	ds_read_b64 v[236:237], v196 offset:16384
	s_waitcnt lgkmcnt(3)
	v_lshlrev_b32_e32 v244, 16, v238
	v_and_b32_e32 v245, 0xffff0000, v238
	v_lshlrev_b32_e32 v246, 16, v239
	v_and_b32_e32 v247, 0xffff0000, v239
	v_mul_f32_e32 v248, v178, v244
	v_mul_f32_e32 v249, v179, v245
	v_mul_f32_e32 v250, v180, v246
	v_mul_f32_e32 v251, v181, v247
	v_lshlrev_b32_e32 v244, 16, v240
	v_and_b32_e32 v245, 0xffff0000, v240
	v_lshlrev_b32_e32 v246, 16, v241
	v_and_b32_e32 v247, 0xffff0000, v241
	v_fmac_f32_e32 v248, v182, v244
	v_fmac_f32_e32 v249, v183, v245
	v_fmac_f32_e32 v250, v184, v246
	v_fmac_f32_e32 v251, v185, v247
	v_lshlrev_b32_e32 v244, 16, v242
	v_and_b32_e32 v245, 0xffff0000, v242
	v_lshlrev_b32_e32 v246, 16, v243
	v_and_b32_e32 v247, 0xffff0000, v243
	v_fmac_f32_e32 v248, v186, v244
	v_fmac_f32_e32 v249, v187, v245
	v_fmac_f32_e32 v250, v188, v246
	v_fmac_f32_e32 v251, v189, v247
	v_mul_f32_e32 v244, 0xbfb8aa3b, v248
	v_mul_f32_e32 v245, 0xbfb8aa3b, v249
	v_mul_f32_e32 v246, 0xbfb8aa3b, v250
	v_mul_f32_e32 v247, 0xbfb8aa3b, v251
	v_exp_f32_e32 v244, v244
	v_exp_f32_e32 v245, v245
	v_exp_f32_e32 v246, v246
	v_exp_f32_e32 v247, v247
	v_add_f32_e32 v244, 1.0, v244
	v_add_f32_e32 v245, 1.0, v245
	v_add_f32_e32 v246, 1.0, v246
	v_add_f32_e32 v247, 1.0, v247
	v_rcp_f32_e32 v244, v244
	v_rcp_f32_e32 v245, v245
	v_rcp_f32_e32 v246, v246
	v_rcp_f32_e32 v247, v247
	v_mul_f32_e32 v248, v248, v244
	v_mul_f32_e32 v249, v249, v245
	v_mul_f32_e32 v250, v250, v246
	v_mul_f32_e32 v251, v251, v247
	v_mul_f32_e32 v98, v98, v248
	v_mul_f32_e32 v99, v99, v249
	v_mul_f32_e32 v100, v100, v250
	v_mul_f32_e32 v101, v101, v251
	v_cvt_pk_bf16_f32 v98, v98, v99
	v_cvt_pk_bf16_f32 v99, v100, v101
	ds_read_b64 v[238:239], v191 offset:8192
	ds_read_b64 v[240:241], v195 offset:16384
	ds_read_b64 v[242:243], v197 offset:16384
	s_waitcnt lgkmcnt(3)
	v_lshlrev_b32_e32 v244, 16, v232
	v_and_b32_e32 v245, 0xffff0000, v232
	v_lshlrev_b32_e32 v246, 16, v233
	v_and_b32_e32 v247, 0xffff0000, v233
	v_mul_f32_e32 v248, v142, v244
	v_mul_f32_e32 v249, v143, v245
	v_mul_f32_e32 v250, v144, v246
	v_mul_f32_e32 v251, v145, v247
	v_lshlrev_b32_e32 v244, 16, v234
	v_and_b32_e32 v245, 0xffff0000, v234
	v_lshlrev_b32_e32 v246, 16, v235
	v_and_b32_e32 v247, 0xffff0000, v235
	v_fmac_f32_e32 v248, v146, v244
	v_fmac_f32_e32 v249, v147, v245
	v_fmac_f32_e32 v250, v148, v246
	v_fmac_f32_e32 v251, v149, v247
	v_lshlrev_b32_e32 v244, 16, v236
	v_and_b32_e32 v245, 0xffff0000, v236
	v_lshlrev_b32_e32 v246, 16, v237
	v_and_b32_e32 v247, 0xffff0000, v237
	v_fmac_f32_e32 v248, v150, v244
	v_fmac_f32_e32 v249, v151, v245
	v_fmac_f32_e32 v250, v152, v246
	v_fmac_f32_e32 v251, v153, v247
	v_mul_f32_e32 v244, 0xbfb8aa3b, v248
	v_mul_f32_e32 v245, 0xbfb8aa3b, v249
	v_mul_f32_e32 v246, 0xbfb8aa3b, v250
	v_mul_f32_e32 v247, 0xbfb8aa3b, v251
	v_exp_f32_e32 v244, v244
	v_exp_f32_e32 v245, v245
	v_exp_f32_e32 v246, v246
	v_exp_f32_e32 v247, v247
	v_add_f32_e32 v244, 1.0, v244
	v_add_f32_e32 v245, 1.0, v245
	v_add_f32_e32 v246, 1.0, v246
	v_add_f32_e32 v247, 1.0, v247
	v_rcp_f32_e32 v244, v244
	v_rcp_f32_e32 v245, v245
	v_rcp_f32_e32 v246, v246
	v_rcp_f32_e32 v247, v247
	v_mul_f32_e32 v248, v248, v244
	v_mul_f32_e32 v249, v249, v245
	v_mul_f32_e32 v250, v250, v246
	v_mul_f32_e32 v251, v251, v247
	v_mul_f32_e32 v94, v94, v248
	v_mul_f32_e32 v95, v95, v249
	v_mul_f32_e32 v96, v96, v250
	v_mul_f32_e32 v97, v97, v251
	v_cvt_pk_bf16_f32 v94, v94, v95
	v_cvt_pk_bf16_f32 v95, v96, v97
	ds_read_b64 v[232:233], v190 offset:8448
	ds_read_b64 v[234:235], v194 offset:16640
	ds_read_b64 v[236:237], v196 offset:16640
	s_waitcnt lgkmcnt(3)
	v_lshlrev_b32_e32 v244, 16, v238
	v_and_b32_e32 v245, 0xffff0000, v238
	v_lshlrev_b32_e32 v246, 16, v239
	v_and_b32_e32 v247, 0xffff0000, v239
	v_mul_f32_e32 v248, v154, v244
	v_mul_f32_e32 v249, v155, v245
	v_mul_f32_e32 v250, v156, v246
	v_mul_f32_e32 v251, v157, v247
	v_lshlrev_b32_e32 v244, 16, v240
	v_and_b32_e32 v245, 0xffff0000, v240
	v_lshlrev_b32_e32 v246, 16, v241
	v_and_b32_e32 v247, 0xffff0000, v241
	v_fmac_f32_e32 v248, v158, v244
	v_fmac_f32_e32 v249, v159, v245
	v_fmac_f32_e32 v250, v160, v246
	v_fmac_f32_e32 v251, v161, v247
	v_lshlrev_b32_e32 v244, 16, v242
	v_and_b32_e32 v245, 0xffff0000, v242
	v_lshlrev_b32_e32 v246, 16, v243
	v_and_b32_e32 v247, 0xffff0000, v243
	v_fmac_f32_e32 v248, v162, v244
	v_fmac_f32_e32 v249, v163, v245
	v_fmac_f32_e32 v250, v164, v246
	v_fmac_f32_e32 v251, v165, v247
	v_mul_f32_e32 v244, 0xbfb8aa3b, v248
	v_mul_f32_e32 v245, 0xbfb8aa3b, v249
	v_mul_f32_e32 v246, 0xbfb8aa3b, v250
	v_mul_f32_e32 v247, 0xbfb8aa3b, v251
	v_exp_f32_e32 v244, v244
	v_exp_f32_e32 v245, v245
	v_exp_f32_e32 v246, v246
	v_exp_f32_e32 v247, v247
	v_add_f32_e32 v244, 1.0, v244
	v_add_f32_e32 v245, 1.0, v245
	v_add_f32_e32 v246, 1.0, v246
	v_add_f32_e32 v247, 1.0, v247
	v_rcp_f32_e32 v244, v244
	v_rcp_f32_e32 v245, v245
	v_rcp_f32_e32 v246, v246
	v_rcp_f32_e32 v247, v247
	v_mul_f32_e32 v248, v248, v244
	v_mul_f32_e32 v249, v249, v245
	v_mul_f32_e32 v250, v250, v246
	v_mul_f32_e32 v251, v251, v247
	v_mul_f32_e32 v90, v90, v248
	v_mul_f32_e32 v91, v91, v249
	v_mul_f32_e32 v92, v92, v250
	v_mul_f32_e32 v93, v93, v251
	v_cvt_pk_bf16_f32 v90, v90, v91
	v_cvt_pk_bf16_f32 v91, v92, v93
	ds_read_b64 v[238:239], v191 offset:8448
	ds_read_b64 v[240:241], v195 offset:16640
	ds_read_b64 v[242:243], v197 offset:16640
	s_waitcnt lgkmcnt(3)
	v_lshlrev_b32_e32 v244, 16, v232
	v_and_b32_e32 v245, 0xffff0000, v232
	v_lshlrev_b32_e32 v246, 16, v233
	v_and_b32_e32 v247, 0xffff0000, v233
	v_mul_f32_e32 v248, v166, v244
	v_mul_f32_e32 v249, v167, v245
	v_mul_f32_e32 v250, v168, v246
	v_mul_f32_e32 v251, v169, v247
	v_lshlrev_b32_e32 v244, 16, v234
	v_and_b32_e32 v245, 0xffff0000, v234
	v_lshlrev_b32_e32 v246, 16, v235
	v_and_b32_e32 v247, 0xffff0000, v235
	v_fmac_f32_e32 v248, v170, v244
	v_fmac_f32_e32 v249, v171, v245
	v_fmac_f32_e32 v250, v172, v246
	v_fmac_f32_e32 v251, v173, v247
	v_lshlrev_b32_e32 v244, 16, v236
	v_and_b32_e32 v245, 0xffff0000, v236
	v_lshlrev_b32_e32 v246, 16, v237
	v_and_b32_e32 v247, 0xffff0000, v237
	v_fmac_f32_e32 v248, v174, v244
	v_fmac_f32_e32 v249, v175, v245
	v_fmac_f32_e32 v250, v176, v246
	v_fmac_f32_e32 v251, v177, v247
	v_mul_f32_e32 v244, 0xbfb8aa3b, v248
	v_mul_f32_e32 v245, 0xbfb8aa3b, v249
	v_mul_f32_e32 v246, 0xbfb8aa3b, v250
	v_mul_f32_e32 v247, 0xbfb8aa3b, v251
	v_exp_f32_e32 v244, v244
	v_exp_f32_e32 v245, v245
	v_exp_f32_e32 v246, v246
	v_exp_f32_e32 v247, v247
	v_add_f32_e32 v244, 1.0, v244
	v_add_f32_e32 v245, 1.0, v245
	v_add_f32_e32 v246, 1.0, v246
	v_add_f32_e32 v247, 1.0, v247
	v_rcp_f32_e32 v244, v244
	v_rcp_f32_e32 v245, v245
	v_rcp_f32_e32 v246, v246
	v_rcp_f32_e32 v247, v247
	v_mul_f32_e32 v248, v248, v244
	v_mul_f32_e32 v249, v249, v245
	v_mul_f32_e32 v250, v250, v246
	v_mul_f32_e32 v251, v251, v247
	v_mul_f32_e32 v86, v86, v248
	v_mul_f32_e32 v87, v87, v249
	v_mul_f32_e32 v88, v88, v250
	v_mul_f32_e32 v89, v89, v251
	v_cvt_pk_bf16_f32 v86, v86, v87
	v_cvt_pk_bf16_f32 v87, v88, v89
	ds_read_b64 v[232:233], v190 offset:16384
	ds_read_b64 v[234:235], v194 offset:24576
	ds_read_b64 v[236:237], v196 offset:24576
	s_waitcnt lgkmcnt(3)
	v_lshlrev_b32_e32 v244, 16, v238
	v_and_b32_e32 v245, 0xffff0000, v238
	v_lshlrev_b32_e32 v246, 16, v239
	v_and_b32_e32 v247, 0xffff0000, v239
	v_mul_f32_e32 v248, v178, v244
	v_mul_f32_e32 v249, v179, v245
	v_mul_f32_e32 v250, v180, v246
	v_mul_f32_e32 v251, v181, v247
	v_lshlrev_b32_e32 v244, 16, v240
	v_and_b32_e32 v245, 0xffff0000, v240
	v_lshlrev_b32_e32 v246, 16, v241
	v_and_b32_e32 v247, 0xffff0000, v241
	v_fmac_f32_e32 v248, v182, v244
	v_fmac_f32_e32 v249, v183, v245
	v_fmac_f32_e32 v250, v184, v246
	v_fmac_f32_e32 v251, v185, v247
	v_lshlrev_b32_e32 v244, 16, v242
	v_and_b32_e32 v245, 0xffff0000, v242
	v_lshlrev_b32_e32 v246, 16, v243
	v_and_b32_e32 v247, 0xffff0000, v243
	v_fmac_f32_e32 v248, v186, v244
	v_fmac_f32_e32 v249, v187, v245
	v_fmac_f32_e32 v250, v188, v246
	v_fmac_f32_e32 v251, v189, v247
	v_mul_f32_e32 v244, 0xbfb8aa3b, v248
	v_mul_f32_e32 v245, 0xbfb8aa3b, v249
	v_mul_f32_e32 v246, 0xbfb8aa3b, v250
	v_mul_f32_e32 v247, 0xbfb8aa3b, v251
	v_exp_f32_e32 v244, v244
	v_exp_f32_e32 v245, v245
	v_exp_f32_e32 v246, v246
	v_exp_f32_e32 v247, v247
	v_add_f32_e32 v244, 1.0, v244
	v_add_f32_e32 v245, 1.0, v245
	v_add_f32_e32 v246, 1.0, v246
	v_add_f32_e32 v247, 1.0, v247
	v_rcp_f32_e32 v244, v244
	v_rcp_f32_e32 v245, v245
	v_rcp_f32_e32 v246, v246
	v_rcp_f32_e32 v247, v247
	v_mul_f32_e32 v248, v248, v244
	v_mul_f32_e32 v249, v249, v245
	v_mul_f32_e32 v250, v250, v246
	v_mul_f32_e32 v251, v251, v247
	v_mul_f32_e32 v82, v82, v248
	v_mul_f32_e32 v83, v83, v249
	v_mul_f32_e32 v84, v84, v250
	v_mul_f32_e32 v85, v85, v251
	v_cvt_pk_bf16_f32 v82, v82, v83
	v_cvt_pk_bf16_f32 v83, v84, v85
	ds_read_b64 v[238:239], v191 offset:16384
	ds_read_b64 v[240:241], v195 offset:24576
	ds_read_b64 v[242:243], v197 offset:24576
	s_waitcnt lgkmcnt(3)
	v_lshlrev_b32_e32 v244, 16, v232
	v_and_b32_e32 v245, 0xffff0000, v232
	v_lshlrev_b32_e32 v246, 16, v233
	v_and_b32_e32 v247, 0xffff0000, v233
	v_mul_f32_e32 v248, v142, v244
	v_mul_f32_e32 v249, v143, v245
	v_mul_f32_e32 v250, v144, v246
	v_mul_f32_e32 v251, v145, v247
	v_lshlrev_b32_e32 v244, 16, v234
	v_and_b32_e32 v245, 0xffff0000, v234
	v_lshlrev_b32_e32 v246, 16, v235
	v_and_b32_e32 v247, 0xffff0000, v235
	v_fmac_f32_e32 v248, v146, v244
	v_fmac_f32_e32 v249, v147, v245
	v_fmac_f32_e32 v250, v148, v246
	v_fmac_f32_e32 v251, v149, v247
	v_lshlrev_b32_e32 v244, 16, v236
	v_and_b32_e32 v245, 0xffff0000, v236
	v_lshlrev_b32_e32 v246, 16, v237
	v_and_b32_e32 v247, 0xffff0000, v237
	v_fmac_f32_e32 v248, v150, v244
	v_fmac_f32_e32 v249, v151, v245
	v_fmac_f32_e32 v250, v152, v246
	v_fmac_f32_e32 v251, v153, v247
	v_mul_f32_e32 v244, 0xbfb8aa3b, v248
	v_mul_f32_e32 v245, 0xbfb8aa3b, v249
	v_mul_f32_e32 v246, 0xbfb8aa3b, v250
	v_mul_f32_e32 v247, 0xbfb8aa3b, v251
	v_exp_f32_e32 v244, v244
	v_exp_f32_e32 v245, v245
	v_exp_f32_e32 v246, v246
	v_exp_f32_e32 v247, v247
	v_add_f32_e32 v244, 1.0, v244
	v_add_f32_e32 v245, 1.0, v245
	v_add_f32_e32 v246, 1.0, v246
	v_add_f32_e32 v247, 1.0, v247
	v_rcp_f32_e32 v244, v244
	v_rcp_f32_e32 v245, v245
	v_rcp_f32_e32 v246, v246
	v_rcp_f32_e32 v247, v247
	v_mul_f32_e32 v248, v248, v244
	v_mul_f32_e32 v249, v249, v245
	v_mul_f32_e32 v250, v250, v246
	v_mul_f32_e32 v251, v251, v247
	v_mul_f32_e32 v78, v78, v248
	v_mul_f32_e32 v79, v79, v249
	v_mul_f32_e32 v80, v80, v250
	v_mul_f32_e32 v81, v81, v251
	v_cvt_pk_bf16_f32 v78, v78, v79
	v_cvt_pk_bf16_f32 v79, v80, v81
	ds_read_b64 v[232:233], v190 offset:16640
	ds_read_b64 v[234:235], v194 offset:24832
	ds_read_b64 v[236:237], v196 offset:24832
	s_waitcnt lgkmcnt(3)
	v_lshlrev_b32_e32 v244, 16, v238
	v_and_b32_e32 v245, 0xffff0000, v238
	v_lshlrev_b32_e32 v246, 16, v239
	v_and_b32_e32 v247, 0xffff0000, v239
	v_mul_f32_e32 v248, v154, v244
	v_mul_f32_e32 v249, v155, v245
	v_mul_f32_e32 v250, v156, v246
	v_mul_f32_e32 v251, v157, v247
	v_lshlrev_b32_e32 v244, 16, v240
	v_and_b32_e32 v245, 0xffff0000, v240
	v_lshlrev_b32_e32 v246, 16, v241
	v_and_b32_e32 v247, 0xffff0000, v241
	v_fmac_f32_e32 v248, v158, v244
	v_fmac_f32_e32 v249, v159, v245
	v_fmac_f32_e32 v250, v160, v246
	v_fmac_f32_e32 v251, v161, v247
	v_lshlrev_b32_e32 v244, 16, v242
	v_and_b32_e32 v245, 0xffff0000, v242
	v_lshlrev_b32_e32 v246, 16, v243
	v_and_b32_e32 v247, 0xffff0000, v243
	v_fmac_f32_e32 v248, v162, v244
	v_fmac_f32_e32 v249, v163, v245
	v_fmac_f32_e32 v250, v164, v246
	v_fmac_f32_e32 v251, v165, v247
	v_mul_f32_e32 v244, 0xbfb8aa3b, v248
	v_mul_f32_e32 v245, 0xbfb8aa3b, v249
	v_mul_f32_e32 v246, 0xbfb8aa3b, v250
	v_mul_f32_e32 v247, 0xbfb8aa3b, v251
	v_exp_f32_e32 v244, v244
	v_exp_f32_e32 v245, v245
	v_exp_f32_e32 v246, v246
	v_exp_f32_e32 v247, v247
	v_add_f32_e32 v244, 1.0, v244
	v_add_f32_e32 v245, 1.0, v245
	v_add_f32_e32 v246, 1.0, v246
	v_add_f32_e32 v247, 1.0, v247
	v_rcp_f32_e32 v244, v244
	v_rcp_f32_e32 v245, v245
	v_rcp_f32_e32 v246, v246
	v_rcp_f32_e32 v247, v247
	v_mul_f32_e32 v248, v248, v244
	v_mul_f32_e32 v249, v249, v245
	v_mul_f32_e32 v250, v250, v246
	v_mul_f32_e32 v251, v251, v247
	v_mul_f32_e32 v74, v74, v248
	v_mul_f32_e32 v75, v75, v249
	v_mul_f32_e32 v76, v76, v250
	v_mul_f32_e32 v77, v77, v251
	v_cvt_pk_bf16_f32 v74, v74, v75
	v_cvt_pk_bf16_f32 v75, v76, v77
	ds_read_b64 v[238:239], v191 offset:16640
	ds_read_b64 v[240:241], v195 offset:24832
	ds_read_b64 v[242:243], v197 offset:24832
	s_waitcnt lgkmcnt(3)
	v_lshlrev_b32_e32 v244, 16, v232
	v_and_b32_e32 v245, 0xffff0000, v232
	v_lshlrev_b32_e32 v246, 16, v233
	v_and_b32_e32 v247, 0xffff0000, v233
	v_mul_f32_e32 v248, v166, v244
	v_mul_f32_e32 v249, v167, v245
	v_mul_f32_e32 v250, v168, v246
	v_mul_f32_e32 v251, v169, v247
	v_lshlrev_b32_e32 v244, 16, v234
	v_and_b32_e32 v245, 0xffff0000, v234
	v_lshlrev_b32_e32 v246, 16, v235
	v_and_b32_e32 v247, 0xffff0000, v235
	v_fmac_f32_e32 v248, v170, v244
	v_fmac_f32_e32 v249, v171, v245
	v_fmac_f32_e32 v250, v172, v246
	v_fmac_f32_e32 v251, v173, v247
	v_lshlrev_b32_e32 v244, 16, v236
	v_and_b32_e32 v245, 0xffff0000, v236
	v_lshlrev_b32_e32 v246, 16, v237
	v_and_b32_e32 v247, 0xffff0000, v237
	v_fmac_f32_e32 v248, v174, v244
	v_fmac_f32_e32 v249, v175, v245
	v_fmac_f32_e32 v250, v176, v246
	v_fmac_f32_e32 v251, v177, v247
	v_mul_f32_e32 v244, 0xbfb8aa3b, v248
	v_mul_f32_e32 v245, 0xbfb8aa3b, v249
	v_mul_f32_e32 v246, 0xbfb8aa3b, v250
	v_mul_f32_e32 v247, 0xbfb8aa3b, v251
	v_exp_f32_e32 v244, v244
	v_exp_f32_e32 v245, v245
	v_exp_f32_e32 v246, v246
	v_exp_f32_e32 v247, v247
	v_add_f32_e32 v244, 1.0, v244
	v_add_f32_e32 v245, 1.0, v245
	v_add_f32_e32 v246, 1.0, v246
	v_add_f32_e32 v247, 1.0, v247
	v_rcp_f32_e32 v244, v244
	v_rcp_f32_e32 v245, v245
	v_rcp_f32_e32 v246, v246
	v_rcp_f32_e32 v247, v247
	v_mul_f32_e32 v248, v248, v244
	v_mul_f32_e32 v249, v249, v245
	v_mul_f32_e32 v250, v250, v246
	v_mul_f32_e32 v251, v251, v247
	v_mul_f32_e32 v70, v70, v248
	v_mul_f32_e32 v71, v71, v249
	v_mul_f32_e32 v72, v72, v250
	v_mul_f32_e32 v73, v73, v251
	v_cvt_pk_bf16_f32 v70, v70, v71
	v_cvt_pk_bf16_f32 v71, v72, v73
	ds_read_b64 v[232:233], v198
	ds_read_b64 v[234:235], v200
	ds_read_b64 v[236:237], v202
	s_waitcnt lgkmcnt(3)
	v_lshlrev_b32_e32 v244, 16, v238
	v_and_b32_e32 v245, 0xffff0000, v238
	v_lshlrev_b32_e32 v246, 16, v239
	v_and_b32_e32 v247, 0xffff0000, v239
	v_mul_f32_e32 v248, v178, v244
	v_mul_f32_e32 v249, v179, v245
	v_mul_f32_e32 v250, v180, v246
	v_mul_f32_e32 v251, v181, v247
	v_lshlrev_b32_e32 v244, 16, v240
	v_and_b32_e32 v245, 0xffff0000, v240
	v_lshlrev_b32_e32 v246, 16, v241
	v_and_b32_e32 v247, 0xffff0000, v241
	v_fmac_f32_e32 v248, v182, v244
	v_fmac_f32_e32 v249, v183, v245
	v_fmac_f32_e32 v250, v184, v246
	v_fmac_f32_e32 v251, v185, v247
	v_lshlrev_b32_e32 v244, 16, v242
	v_and_b32_e32 v245, 0xffff0000, v242
	v_lshlrev_b32_e32 v246, 16, v243
	v_and_b32_e32 v247, 0xffff0000, v243
	v_fmac_f32_e32 v248, v186, v244
	v_fmac_f32_e32 v249, v187, v245
	v_fmac_f32_e32 v250, v188, v246
	v_fmac_f32_e32 v251, v189, v247
	v_mul_f32_e32 v244, 0xbfb8aa3b, v248
	v_mul_f32_e32 v245, 0xbfb8aa3b, v249
	v_mul_f32_e32 v246, 0xbfb8aa3b, v250
	v_mul_f32_e32 v247, 0xbfb8aa3b, v251
	v_exp_f32_e32 v244, v244
	v_exp_f32_e32 v245, v245
	v_exp_f32_e32 v246, v246
	v_exp_f32_e32 v247, v247
	v_add_f32_e32 v244, 1.0, v244
	v_add_f32_e32 v245, 1.0, v245
	v_add_f32_e32 v246, 1.0, v246
	v_add_f32_e32 v247, 1.0, v247
	v_rcp_f32_e32 v244, v244
	v_rcp_f32_e32 v245, v245
	v_rcp_f32_e32 v246, v246
	v_rcp_f32_e32 v247, v247
	v_mul_f32_e32 v248, v248, v244
	v_mul_f32_e32 v249, v249, v245
	v_mul_f32_e32 v250, v250, v246
	v_mul_f32_e32 v251, v251, v247
	v_mul_f32_e32 v66, v66, v248
	v_mul_f32_e32 v67, v67, v249
	v_mul_f32_e32 v68, v68, v250
	v_mul_f32_e32 v69, v69, v251
	v_cvt_pk_bf16_f32 v66, v66, v67
	v_cvt_pk_bf16_f32 v67, v68, v69
	ds_read_b64 v[238:239], v199
	ds_read_b64 v[240:241], v201
	ds_read_b64 v[242:243], v203
	s_waitcnt lgkmcnt(3)
	v_lshlrev_b32_e32 v244, 16, v232
	v_and_b32_e32 v245, 0xffff0000, v232
	v_lshlrev_b32_e32 v246, 16, v233
	v_and_b32_e32 v247, 0xffff0000, v233
	v_mul_f32_e32 v248, v142, v244
	v_mul_f32_e32 v249, v143, v245
	v_mul_f32_e32 v250, v144, v246
	v_mul_f32_e32 v251, v145, v247
	v_lshlrev_b32_e32 v244, 16, v234
	v_and_b32_e32 v245, 0xffff0000, v234
	v_lshlrev_b32_e32 v246, 16, v235
	v_and_b32_e32 v247, 0xffff0000, v235
	v_fmac_f32_e32 v248, v146, v244
	v_fmac_f32_e32 v249, v147, v245
	v_fmac_f32_e32 v250, v148, v246
	v_fmac_f32_e32 v251, v149, v247
	v_lshlrev_b32_e32 v244, 16, v236
	v_and_b32_e32 v245, 0xffff0000, v236
	v_lshlrev_b32_e32 v246, 16, v237
	v_and_b32_e32 v247, 0xffff0000, v237
	v_fmac_f32_e32 v248, v150, v244
	v_fmac_f32_e32 v249, v151, v245
	v_fmac_f32_e32 v250, v152, v246
	v_fmac_f32_e32 v251, v153, v247
	v_mul_f32_e32 v244, 0xbfb8aa3b, v248
	v_mul_f32_e32 v245, 0xbfb8aa3b, v249
	v_mul_f32_e32 v246, 0xbfb8aa3b, v250
	v_mul_f32_e32 v247, 0xbfb8aa3b, v251
	v_exp_f32_e32 v244, v244
	v_exp_f32_e32 v245, v245
	v_exp_f32_e32 v246, v246
	v_exp_f32_e32 v247, v247
	v_add_f32_e32 v244, 1.0, v244
	v_add_f32_e32 v245, 1.0, v245
	v_add_f32_e32 v246, 1.0, v246
	v_add_f32_e32 v247, 1.0, v247
	v_rcp_f32_e32 v244, v244
	v_rcp_f32_e32 v245, v245
	v_rcp_f32_e32 v246, v246
	v_rcp_f32_e32 v247, v247
	v_mul_f32_e32 v248, v248, v244
	v_mul_f32_e32 v249, v249, v245
	v_mul_f32_e32 v250, v250, v246
	v_mul_f32_e32 v251, v251, v247
	v_mul_f32_e32 v62, v62, v248
	v_mul_f32_e32 v63, v63, v249
	v_mul_f32_e32 v64, v64, v250
	v_mul_f32_e32 v65, v65, v251
	v_cvt_pk_bf16_f32 v62, v62, v63
	v_cvt_pk_bf16_f32 v63, v64, v65
	ds_read_b64 v[232:233], v198 offset:256
	ds_read_b64 v[234:235], v200 offset:256
	ds_read_b64 v[236:237], v202 offset:256
	s_waitcnt lgkmcnt(3)
	v_lshlrev_b32_e32 v244, 16, v238
	v_and_b32_e32 v245, 0xffff0000, v238
	v_lshlrev_b32_e32 v246, 16, v239
	v_and_b32_e32 v247, 0xffff0000, v239
	v_mul_f32_e32 v248, v154, v244
	v_mul_f32_e32 v249, v155, v245
	v_mul_f32_e32 v250, v156, v246
	v_mul_f32_e32 v251, v157, v247
	v_lshlrev_b32_e32 v244, 16, v240
	v_and_b32_e32 v245, 0xffff0000, v240
	v_lshlrev_b32_e32 v246, 16, v241
	v_and_b32_e32 v247, 0xffff0000, v241
	v_fmac_f32_e32 v248, v158, v244
	v_fmac_f32_e32 v249, v159, v245
	v_fmac_f32_e32 v250, v160, v246
	v_fmac_f32_e32 v251, v161, v247
	v_lshlrev_b32_e32 v244, 16, v242
	v_and_b32_e32 v245, 0xffff0000, v242
	v_lshlrev_b32_e32 v246, 16, v243
	v_and_b32_e32 v247, 0xffff0000, v243
	v_fmac_f32_e32 v248, v162, v244
	v_fmac_f32_e32 v249, v163, v245
	v_fmac_f32_e32 v250, v164, v246
	v_fmac_f32_e32 v251, v165, v247
	v_mul_f32_e32 v244, 0xbfb8aa3b, v248
	v_mul_f32_e32 v245, 0xbfb8aa3b, v249
	v_mul_f32_e32 v246, 0xbfb8aa3b, v250
	v_mul_f32_e32 v247, 0xbfb8aa3b, v251
	v_exp_f32_e32 v244, v244
	v_exp_f32_e32 v245, v245
	v_exp_f32_e32 v246, v246
	v_exp_f32_e32 v247, v247
	v_add_f32_e32 v244, 1.0, v244
	v_add_f32_e32 v245, 1.0, v245
	v_add_f32_e32 v246, 1.0, v246
	v_add_f32_e32 v247, 1.0, v247
	v_rcp_f32_e32 v244, v244
	v_rcp_f32_e32 v245, v245
	v_rcp_f32_e32 v246, v246
	v_rcp_f32_e32 v247, v247
	v_mul_f32_e32 v248, v248, v244
	v_mul_f32_e32 v249, v249, v245
	v_mul_f32_e32 v250, v250, v246
	v_mul_f32_e32 v251, v251, v247
	v_mul_f32_e32 v58, v58, v248
	v_mul_f32_e32 v59, v59, v249
	v_mul_f32_e32 v60, v60, v250
	v_mul_f32_e32 v61, v61, v251
	v_cvt_pk_bf16_f32 v58, v58, v59
	v_cvt_pk_bf16_f32 v59, v60, v61
	ds_read_b64 v[238:239], v199 offset:256
	ds_read_b64 v[240:241], v201 offset:256
	ds_read_b64 v[242:243], v203 offset:256
	s_waitcnt lgkmcnt(3)
	v_lshlrev_b32_e32 v244, 16, v232
	v_and_b32_e32 v245, 0xffff0000, v232
	v_lshlrev_b32_e32 v246, 16, v233
	v_and_b32_e32 v247, 0xffff0000, v233
	v_mul_f32_e32 v248, v166, v244
	v_mul_f32_e32 v249, v167, v245
	v_mul_f32_e32 v250, v168, v246
	v_mul_f32_e32 v251, v169, v247
	v_lshlrev_b32_e32 v244, 16, v234
	v_and_b32_e32 v245, 0xffff0000, v234
	v_lshlrev_b32_e32 v246, 16, v235
	v_and_b32_e32 v247, 0xffff0000, v235
	v_fmac_f32_e32 v248, v170, v244
	v_fmac_f32_e32 v249, v171, v245
	v_fmac_f32_e32 v250, v172, v246
	v_fmac_f32_e32 v251, v173, v247
	v_lshlrev_b32_e32 v244, 16, v236
	v_and_b32_e32 v245, 0xffff0000, v236
	v_lshlrev_b32_e32 v246, 16, v237
	v_and_b32_e32 v247, 0xffff0000, v237
	v_fmac_f32_e32 v248, v174, v244
	v_fmac_f32_e32 v249, v175, v245
	v_fmac_f32_e32 v250, v176, v246
	v_fmac_f32_e32 v251, v177, v247
	v_mul_f32_e32 v244, 0xbfb8aa3b, v248
	v_mul_f32_e32 v245, 0xbfb8aa3b, v249
	v_mul_f32_e32 v246, 0xbfb8aa3b, v250
	v_mul_f32_e32 v247, 0xbfb8aa3b, v251
	v_exp_f32_e32 v244, v244
	v_exp_f32_e32 v245, v245
	v_exp_f32_e32 v246, v246
	v_exp_f32_e32 v247, v247
	v_add_f32_e32 v244, 1.0, v244
	v_add_f32_e32 v245, 1.0, v245
	v_add_f32_e32 v246, 1.0, v246
	v_add_f32_e32 v247, 1.0, v247
	v_rcp_f32_e32 v244, v244
	v_rcp_f32_e32 v245, v245
	v_rcp_f32_e32 v246, v246
	v_rcp_f32_e32 v247, v247
	v_mul_f32_e32 v248, v248, v244
	v_mul_f32_e32 v249, v249, v245
	v_mul_f32_e32 v250, v250, v246
	v_mul_f32_e32 v251, v251, v247
	v_mul_f32_e32 v54, v54, v248
	v_mul_f32_e32 v55, v55, v249
	v_mul_f32_e32 v56, v56, v250
	v_mul_f32_e32 v57, v57, v251
	v_cvt_pk_bf16_f32 v54, v54, v55
	v_cvt_pk_bf16_f32 v55, v56, v57
	ds_read_b64 v[232:233], v198 offset:8192
	ds_read_b64 v[234:235], v200 offset:8192
	ds_read_b64 v[236:237], v202 offset:8192
	s_waitcnt lgkmcnt(3)
	v_lshlrev_b32_e32 v244, 16, v238
	v_and_b32_e32 v245, 0xffff0000, v238
	v_lshlrev_b32_e32 v246, 16, v239
	v_and_b32_e32 v247, 0xffff0000, v239
	v_mul_f32_e32 v248, v178, v244
	v_mul_f32_e32 v249, v179, v245
	v_mul_f32_e32 v250, v180, v246
	v_mul_f32_e32 v251, v181, v247
	v_lshlrev_b32_e32 v244, 16, v240
	v_and_b32_e32 v245, 0xffff0000, v240
	v_lshlrev_b32_e32 v246, 16, v241
	v_and_b32_e32 v247, 0xffff0000, v241
	v_fmac_f32_e32 v248, v182, v244
	v_fmac_f32_e32 v249, v183, v245
	v_fmac_f32_e32 v250, v184, v246
	v_fmac_f32_e32 v251, v185, v247
	v_lshlrev_b32_e32 v244, 16, v242
	v_and_b32_e32 v245, 0xffff0000, v242
	v_lshlrev_b32_e32 v246, 16, v243
	v_and_b32_e32 v247, 0xffff0000, v243
	v_fmac_f32_e32 v248, v186, v244
	v_fmac_f32_e32 v249, v187, v245
	v_fmac_f32_e32 v250, v188, v246
	v_fmac_f32_e32 v251, v189, v247
	v_mul_f32_e32 v244, 0xbfb8aa3b, v248
	v_mul_f32_e32 v245, 0xbfb8aa3b, v249
	v_mul_f32_e32 v246, 0xbfb8aa3b, v250
	v_mul_f32_e32 v247, 0xbfb8aa3b, v251
	v_exp_f32_e32 v244, v244
	v_exp_f32_e32 v245, v245
	v_exp_f32_e32 v246, v246
	v_exp_f32_e32 v247, v247
	v_add_f32_e32 v244, 1.0, v244
	v_add_f32_e32 v245, 1.0, v245
	v_add_f32_e32 v246, 1.0, v246
	v_add_f32_e32 v247, 1.0, v247
	v_rcp_f32_e32 v244, v244
	v_rcp_f32_e32 v245, v245
	v_rcp_f32_e32 v246, v246
	v_rcp_f32_e32 v247, v247
	v_mul_f32_e32 v248, v248, v244
	v_mul_f32_e32 v249, v249, v245
	v_mul_f32_e32 v250, v250, v246
	v_mul_f32_e32 v251, v251, v247
	v_mul_f32_e32 v50, v50, v248
	v_mul_f32_e32 v51, v51, v249
	v_mul_f32_e32 v52, v52, v250
	v_mul_f32_e32 v53, v53, v251
	v_cvt_pk_bf16_f32 v50, v50, v51
	v_cvt_pk_bf16_f32 v51, v52, v53
	ds_read_b64 v[238:239], v199 offset:8192
	ds_read_b64 v[240:241], v201 offset:8192
	ds_read_b64 v[242:243], v203 offset:8192
	s_waitcnt lgkmcnt(3)
	v_lshlrev_b32_e32 v244, 16, v232
	v_and_b32_e32 v245, 0xffff0000, v232
	v_lshlrev_b32_e32 v246, 16, v233
	v_and_b32_e32 v247, 0xffff0000, v233
	v_mul_f32_e32 v248, v142, v244
	v_mul_f32_e32 v249, v143, v245
	v_mul_f32_e32 v250, v144, v246
	v_mul_f32_e32 v251, v145, v247
	v_lshlrev_b32_e32 v244, 16, v234
	v_and_b32_e32 v245, 0xffff0000, v234
	v_lshlrev_b32_e32 v246, 16, v235
	v_and_b32_e32 v247, 0xffff0000, v235
	v_fmac_f32_e32 v248, v146, v244
	v_fmac_f32_e32 v249, v147, v245
	v_fmac_f32_e32 v250, v148, v246
	v_fmac_f32_e32 v251, v149, v247
	v_lshlrev_b32_e32 v244, 16, v236
	v_and_b32_e32 v245, 0xffff0000, v236
	v_lshlrev_b32_e32 v246, 16, v237
	v_and_b32_e32 v247, 0xffff0000, v237
	v_fmac_f32_e32 v248, v150, v244
	v_fmac_f32_e32 v249, v151, v245
	v_fmac_f32_e32 v250, v152, v246
	v_fmac_f32_e32 v251, v153, v247
	v_mul_f32_e32 v244, 0xbfb8aa3b, v248
	v_mul_f32_e32 v245, 0xbfb8aa3b, v249
	v_mul_f32_e32 v246, 0xbfb8aa3b, v250
	v_mul_f32_e32 v247, 0xbfb8aa3b, v251
	v_exp_f32_e32 v244, v244
	v_exp_f32_e32 v245, v245
	v_exp_f32_e32 v246, v246
	v_exp_f32_e32 v247, v247
	v_add_f32_e32 v244, 1.0, v244
	v_add_f32_e32 v245, 1.0, v245
	v_add_f32_e32 v246, 1.0, v246
	v_add_f32_e32 v247, 1.0, v247
	v_rcp_f32_e32 v244, v244
	v_rcp_f32_e32 v245, v245
	v_rcp_f32_e32 v246, v246
	v_rcp_f32_e32 v247, v247
	v_mul_f32_e32 v248, v248, v244
	v_mul_f32_e32 v249, v249, v245
	v_mul_f32_e32 v250, v250, v246
	v_mul_f32_e32 v251, v251, v247
	v_mul_f32_e32 v46, v46, v248
	v_mul_f32_e32 v47, v47, v249
	v_mul_f32_e32 v48, v48, v250
	v_mul_f32_e32 v49, v49, v251
	v_cvt_pk_bf16_f32 v46, v46, v47
	v_cvt_pk_bf16_f32 v47, v48, v49
	ds_read_b64 v[232:233], v198 offset:8448
	ds_read_b64 v[234:235], v200 offset:8448
	ds_read_b64 v[236:237], v202 offset:8448
	s_waitcnt lgkmcnt(3)
	v_lshlrev_b32_e32 v244, 16, v238
	v_and_b32_e32 v245, 0xffff0000, v238
	v_lshlrev_b32_e32 v246, 16, v239
	v_and_b32_e32 v247, 0xffff0000, v239
	v_mul_f32_e32 v248, v154, v244
	v_mul_f32_e32 v249, v155, v245
	v_mul_f32_e32 v250, v156, v246
	v_mul_f32_e32 v251, v157, v247
	v_lshlrev_b32_e32 v244, 16, v240
	v_and_b32_e32 v245, 0xffff0000, v240
	v_lshlrev_b32_e32 v246, 16, v241
	v_and_b32_e32 v247, 0xffff0000, v241
	v_fmac_f32_e32 v248, v158, v244
	v_fmac_f32_e32 v249, v159, v245
	v_fmac_f32_e32 v250, v160, v246
	v_fmac_f32_e32 v251, v161, v247
	v_lshlrev_b32_e32 v244, 16, v242
	v_and_b32_e32 v245, 0xffff0000, v242
	v_lshlrev_b32_e32 v246, 16, v243
	v_and_b32_e32 v247, 0xffff0000, v243
	v_fmac_f32_e32 v248, v162, v244
	v_fmac_f32_e32 v249, v163, v245
	v_fmac_f32_e32 v250, v164, v246
	v_fmac_f32_e32 v251, v165, v247
	v_mul_f32_e32 v244, 0xbfb8aa3b, v248
	v_mul_f32_e32 v245, 0xbfb8aa3b, v249
	v_mul_f32_e32 v246, 0xbfb8aa3b, v250
	v_mul_f32_e32 v247, 0xbfb8aa3b, v251
	v_exp_f32_e32 v244, v244
	v_exp_f32_e32 v245, v245
	v_exp_f32_e32 v246, v246
	v_exp_f32_e32 v247, v247
	v_add_f32_e32 v244, 1.0, v244
	v_add_f32_e32 v245, 1.0, v245
	v_add_f32_e32 v246, 1.0, v246
	v_add_f32_e32 v247, 1.0, v247
	v_rcp_f32_e32 v244, v244
	v_rcp_f32_e32 v245, v245
	v_rcp_f32_e32 v246, v246
	v_rcp_f32_e32 v247, v247
	v_mul_f32_e32 v248, v248, v244
	v_mul_f32_e32 v249, v249, v245
	v_mul_f32_e32 v250, v250, v246
	v_mul_f32_e32 v251, v251, v247
	v_mul_f32_e32 v42, v42, v248
	v_mul_f32_e32 v43, v43, v249
	v_mul_f32_e32 v44, v44, v250
	v_mul_f32_e32 v45, v45, v251
	v_cvt_pk_bf16_f32 v42, v42, v43
	v_cvt_pk_bf16_f32 v43, v44, v45
	ds_read_b64 v[238:239], v199 offset:8448
	ds_read_b64 v[240:241], v201 offset:8448
	ds_read_b64 v[242:243], v203 offset:8448
	s_waitcnt lgkmcnt(3)
	v_lshlrev_b32_e32 v244, 16, v232
	v_and_b32_e32 v245, 0xffff0000, v232
	v_lshlrev_b32_e32 v246, 16, v233
	v_and_b32_e32 v247, 0xffff0000, v233
	v_mul_f32_e32 v248, v166, v244
	v_mul_f32_e32 v249, v167, v245
	v_mul_f32_e32 v250, v168, v246
	v_mul_f32_e32 v251, v169, v247
	v_lshlrev_b32_e32 v244, 16, v234
	v_and_b32_e32 v245, 0xffff0000, v234
	v_lshlrev_b32_e32 v246, 16, v235
	v_and_b32_e32 v247, 0xffff0000, v235
	v_fmac_f32_e32 v248, v170, v244
	v_fmac_f32_e32 v249, v171, v245
	v_fmac_f32_e32 v250, v172, v246
	v_fmac_f32_e32 v251, v173, v247
	v_lshlrev_b32_e32 v244, 16, v236
	v_and_b32_e32 v245, 0xffff0000, v236
	v_lshlrev_b32_e32 v246, 16, v237
	v_and_b32_e32 v247, 0xffff0000, v237
	v_fmac_f32_e32 v248, v174, v244
	v_fmac_f32_e32 v249, v175, v245
	v_fmac_f32_e32 v250, v176, v246
	v_fmac_f32_e32 v251, v177, v247
	v_mul_f32_e32 v244, 0xbfb8aa3b, v248
	v_mul_f32_e32 v245, 0xbfb8aa3b, v249
	v_mul_f32_e32 v246, 0xbfb8aa3b, v250
	v_mul_f32_e32 v247, 0xbfb8aa3b, v251
	v_exp_f32_e32 v244, v244
	v_exp_f32_e32 v245, v245
	v_exp_f32_e32 v246, v246
	v_exp_f32_e32 v247, v247
	v_add_f32_e32 v244, 1.0, v244
	v_add_f32_e32 v245, 1.0, v245
	v_add_f32_e32 v246, 1.0, v246
	v_add_f32_e32 v247, 1.0, v247
	v_rcp_f32_e32 v244, v244
	v_rcp_f32_e32 v245, v245
	v_rcp_f32_e32 v246, v246
	v_rcp_f32_e32 v247, v247
	v_mul_f32_e32 v248, v248, v244
	v_mul_f32_e32 v249, v249, v245
	v_mul_f32_e32 v250, v250, v246
	v_mul_f32_e32 v251, v251, v247
	v_mul_f32_e32 v38, v38, v248
	v_mul_f32_e32 v39, v39, v249
	v_mul_f32_e32 v40, v40, v250
	v_mul_f32_e32 v41, v41, v251
	v_cvt_pk_bf16_f32 v38, v38, v39
	v_cvt_pk_bf16_f32 v39, v40, v41
	ds_read_b64 v[232:233], v198 offset:16384
	ds_read_b64 v[234:235], v200 offset:16384
	ds_read_b64 v[236:237], v202 offset:16384
	s_waitcnt lgkmcnt(3)
	v_lshlrev_b32_e32 v244, 16, v238
	v_and_b32_e32 v245, 0xffff0000, v238
	v_lshlrev_b32_e32 v246, 16, v239
	v_and_b32_e32 v247, 0xffff0000, v239
	v_mul_f32_e32 v248, v178, v244
	v_mul_f32_e32 v249, v179, v245
	v_mul_f32_e32 v250, v180, v246
	v_mul_f32_e32 v251, v181, v247
	v_lshlrev_b32_e32 v244, 16, v240
	v_and_b32_e32 v245, 0xffff0000, v240
	v_lshlrev_b32_e32 v246, 16, v241
	v_and_b32_e32 v247, 0xffff0000, v241
	v_fmac_f32_e32 v248, v182, v244
	v_fmac_f32_e32 v249, v183, v245
	v_fmac_f32_e32 v250, v184, v246
	v_fmac_f32_e32 v251, v185, v247
	v_lshlrev_b32_e32 v244, 16, v242
	v_and_b32_e32 v245, 0xffff0000, v242
	v_lshlrev_b32_e32 v246, 16, v243
	v_and_b32_e32 v247, 0xffff0000, v243
	v_fmac_f32_e32 v248, v186, v244
	v_fmac_f32_e32 v249, v187, v245
	v_fmac_f32_e32 v250, v188, v246
	v_fmac_f32_e32 v251, v189, v247
	v_mul_f32_e32 v244, 0xbfb8aa3b, v248
	v_mul_f32_e32 v245, 0xbfb8aa3b, v249
	v_mul_f32_e32 v246, 0xbfb8aa3b, v250
	v_mul_f32_e32 v247, 0xbfb8aa3b, v251
	v_exp_f32_e32 v244, v244
	v_exp_f32_e32 v245, v245
	v_exp_f32_e32 v246, v246
	v_exp_f32_e32 v247, v247
	v_add_f32_e32 v244, 1.0, v244
	v_add_f32_e32 v245, 1.0, v245
	v_add_f32_e32 v246, 1.0, v246
	v_add_f32_e32 v247, 1.0, v247
	v_rcp_f32_e32 v244, v244
	v_rcp_f32_e32 v245, v245
	v_rcp_f32_e32 v246, v246
	v_rcp_f32_e32 v247, v247
	v_mul_f32_e32 v248, v248, v244
	v_mul_f32_e32 v249, v249, v245
	v_mul_f32_e32 v250, v250, v246
	v_mul_f32_e32 v251, v251, v247
	v_mul_f32_e32 v34, v34, v248
	v_mul_f32_e32 v35, v35, v249
	v_mul_f32_e32 v36, v36, v250
	v_mul_f32_e32 v37, v37, v251
	v_cvt_pk_bf16_f32 v34, v34, v35
	v_cvt_pk_bf16_f32 v35, v36, v37
	ds_read_b64 v[238:239], v199 offset:16384
	ds_read_b64 v[240:241], v201 offset:16384
	ds_read_b64 v[242:243], v203 offset:16384
	s_waitcnt lgkmcnt(3)
	v_lshlrev_b32_e32 v244, 16, v232
	v_and_b32_e32 v245, 0xffff0000, v232
	v_lshlrev_b32_e32 v246, 16, v233
	v_and_b32_e32 v247, 0xffff0000, v233
	v_mul_f32_e32 v248, v142, v244
	v_mul_f32_e32 v249, v143, v245
	v_mul_f32_e32 v250, v144, v246
	v_mul_f32_e32 v251, v145, v247
	v_lshlrev_b32_e32 v244, 16, v234
	v_and_b32_e32 v245, 0xffff0000, v234
	v_lshlrev_b32_e32 v246, 16, v235
	v_and_b32_e32 v247, 0xffff0000, v235
	v_fmac_f32_e32 v248, v146, v244
	v_fmac_f32_e32 v249, v147, v245
	v_fmac_f32_e32 v250, v148, v246
	v_fmac_f32_e32 v251, v149, v247
	v_lshlrev_b32_e32 v244, 16, v236
	v_and_b32_e32 v245, 0xffff0000, v236
	v_lshlrev_b32_e32 v246, 16, v237
	v_and_b32_e32 v247, 0xffff0000, v237
	v_fmac_f32_e32 v248, v150, v244
	v_fmac_f32_e32 v249, v151, v245
	v_fmac_f32_e32 v250, v152, v246
	v_fmac_f32_e32 v251, v153, v247
	v_mul_f32_e32 v244, 0xbfb8aa3b, v248
	v_mul_f32_e32 v245, 0xbfb8aa3b, v249
	v_mul_f32_e32 v246, 0xbfb8aa3b, v250
	v_mul_f32_e32 v247, 0xbfb8aa3b, v251
	v_exp_f32_e32 v244, v244
	v_exp_f32_e32 v245, v245
	v_exp_f32_e32 v246, v246
	v_exp_f32_e32 v247, v247
	v_add_f32_e32 v244, 1.0, v244
	v_add_f32_e32 v245, 1.0, v245
	v_add_f32_e32 v246, 1.0, v246
	v_add_f32_e32 v247, 1.0, v247
	v_rcp_f32_e32 v244, v244
	v_rcp_f32_e32 v245, v245
	v_rcp_f32_e32 v246, v246
	v_rcp_f32_e32 v247, v247
	v_mul_f32_e32 v248, v248, v244
	v_mul_f32_e32 v249, v249, v245
	v_mul_f32_e32 v250, v250, v246
	v_mul_f32_e32 v251, v251, v247
	v_mul_f32_e32 v30, v30, v248
	v_mul_f32_e32 v31, v31, v249
	v_mul_f32_e32 v32, v32, v250
	v_mul_f32_e32 v33, v33, v251
	v_cvt_pk_bf16_f32 v30, v30, v31
	v_cvt_pk_bf16_f32 v31, v32, v33
	ds_read_b64 v[232:233], v198 offset:16640
	ds_read_b64 v[234:235], v200 offset:16640
	ds_read_b64 v[236:237], v202 offset:16640
	s_waitcnt lgkmcnt(3)
	v_lshlrev_b32_e32 v244, 16, v238
	v_and_b32_e32 v245, 0xffff0000, v238
	v_lshlrev_b32_e32 v246, 16, v239
	v_and_b32_e32 v247, 0xffff0000, v239
	v_mul_f32_e32 v248, v154, v244
	v_mul_f32_e32 v249, v155, v245
	v_mul_f32_e32 v250, v156, v246
	v_mul_f32_e32 v251, v157, v247
	v_lshlrev_b32_e32 v244, 16, v240
	v_and_b32_e32 v245, 0xffff0000, v240
	v_lshlrev_b32_e32 v246, 16, v241
	v_and_b32_e32 v247, 0xffff0000, v241
	v_fmac_f32_e32 v248, v158, v244
	v_fmac_f32_e32 v249, v159, v245
	v_fmac_f32_e32 v250, v160, v246
	v_fmac_f32_e32 v251, v161, v247
	v_lshlrev_b32_e32 v244, 16, v242
	v_and_b32_e32 v245, 0xffff0000, v242
	v_lshlrev_b32_e32 v246, 16, v243
	v_and_b32_e32 v247, 0xffff0000, v243
	v_fmac_f32_e32 v248, v162, v244
	v_fmac_f32_e32 v249, v163, v245
	v_fmac_f32_e32 v250, v164, v246
	v_fmac_f32_e32 v251, v165, v247
	v_mul_f32_e32 v244, 0xbfb8aa3b, v248
	v_mul_f32_e32 v245, 0xbfb8aa3b, v249
	v_mul_f32_e32 v246, 0xbfb8aa3b, v250
	v_mul_f32_e32 v247, 0xbfb8aa3b, v251
	v_exp_f32_e32 v244, v244
	v_exp_f32_e32 v245, v245
	v_exp_f32_e32 v246, v246
	v_exp_f32_e32 v247, v247
	v_add_f32_e32 v244, 1.0, v244
	v_add_f32_e32 v245, 1.0, v245
	v_add_f32_e32 v246, 1.0, v246
	v_add_f32_e32 v247, 1.0, v247
	v_rcp_f32_e32 v244, v244
	v_rcp_f32_e32 v245, v245
	v_rcp_f32_e32 v246, v246
	v_rcp_f32_e32 v247, v247
	v_mul_f32_e32 v248, v248, v244
	v_mul_f32_e32 v249, v249, v245
	v_mul_f32_e32 v250, v250, v246
	v_mul_f32_e32 v251, v251, v247
	v_mul_f32_e32 v26, v26, v248
	v_mul_f32_e32 v27, v27, v249
	v_mul_f32_e32 v28, v28, v250
	v_mul_f32_e32 v29, v29, v251
	v_cvt_pk_bf16_f32 v26, v26, v27
	v_cvt_pk_bf16_f32 v27, v28, v29
	ds_read_b64 v[238:239], v199 offset:16640
	ds_read_b64 v[240:241], v201 offset:16640
	ds_read_b64 v[242:243], v203 offset:16640
	s_waitcnt lgkmcnt(3)
	v_lshlrev_b32_e32 v244, 16, v232
	v_and_b32_e32 v245, 0xffff0000, v232
	v_lshlrev_b32_e32 v246, 16, v233
	v_and_b32_e32 v247, 0xffff0000, v233
	v_mul_f32_e32 v248, v166, v244
	v_mul_f32_e32 v249, v167, v245
	v_mul_f32_e32 v250, v168, v246
	v_mul_f32_e32 v251, v169, v247
	v_lshlrev_b32_e32 v244, 16, v234
	v_and_b32_e32 v245, 0xffff0000, v234
	v_lshlrev_b32_e32 v246, 16, v235
	v_and_b32_e32 v247, 0xffff0000, v235
	v_fmac_f32_e32 v248, v170, v244
	v_fmac_f32_e32 v249, v171, v245
	v_fmac_f32_e32 v250, v172, v246
	v_fmac_f32_e32 v251, v173, v247
	v_lshlrev_b32_e32 v244, 16, v236
	v_and_b32_e32 v245, 0xffff0000, v236
	v_lshlrev_b32_e32 v246, 16, v237
	v_and_b32_e32 v247, 0xffff0000, v237
	v_fmac_f32_e32 v248, v174, v244
	v_fmac_f32_e32 v249, v175, v245
	v_fmac_f32_e32 v250, v176, v246
	v_fmac_f32_e32 v251, v177, v247
	v_mul_f32_e32 v244, 0xbfb8aa3b, v248
	v_mul_f32_e32 v245, 0xbfb8aa3b, v249
	v_mul_f32_e32 v246, 0xbfb8aa3b, v250
	v_mul_f32_e32 v247, 0xbfb8aa3b, v251
	v_exp_f32_e32 v244, v244
	v_exp_f32_e32 v245, v245
	v_exp_f32_e32 v246, v246
	v_exp_f32_e32 v247, v247
	v_add_f32_e32 v244, 1.0, v244
	v_add_f32_e32 v245, 1.0, v245
	v_add_f32_e32 v246, 1.0, v246
	v_add_f32_e32 v247, 1.0, v247
	v_rcp_f32_e32 v244, v244
	v_rcp_f32_e32 v245, v245
	v_rcp_f32_e32 v246, v246
	v_rcp_f32_e32 v247, v247
	v_mul_f32_e32 v248, v248, v244
	v_mul_f32_e32 v249, v249, v245
	v_mul_f32_e32 v250, v250, v246
	v_mul_f32_e32 v251, v251, v247
	v_mul_f32_e32 v22, v22, v248
	v_mul_f32_e32 v23, v23, v249
	v_mul_f32_e32 v24, v24, v250
	v_mul_f32_e32 v25, v25, v251
	v_cvt_pk_bf16_f32 v22, v22, v23
	v_cvt_pk_bf16_f32 v23, v24, v25
	ds_read_b64 v[232:233], v198 offset:24576
	ds_read_b64 v[234:235], v200 offset:24576
	ds_read_b64 v[236:237], v204
	s_waitcnt lgkmcnt(3)
	v_lshlrev_b32_e32 v244, 16, v238
	v_and_b32_e32 v245, 0xffff0000, v238
	v_lshlrev_b32_e32 v246, 16, v239
	v_and_b32_e32 v247, 0xffff0000, v239
	v_mul_f32_e32 v248, v178, v244
	v_mul_f32_e32 v249, v179, v245
	v_mul_f32_e32 v250, v180, v246
	v_mul_f32_e32 v251, v181, v247
	v_lshlrev_b32_e32 v244, 16, v240
	v_and_b32_e32 v245, 0xffff0000, v240
	v_lshlrev_b32_e32 v246, 16, v241
	v_and_b32_e32 v247, 0xffff0000, v241
	v_fmac_f32_e32 v248, v182, v244
	v_fmac_f32_e32 v249, v183, v245
	v_fmac_f32_e32 v250, v184, v246
	v_fmac_f32_e32 v251, v185, v247
	v_lshlrev_b32_e32 v244, 16, v242
	v_and_b32_e32 v245, 0xffff0000, v242
	v_lshlrev_b32_e32 v246, 16, v243
	v_and_b32_e32 v247, 0xffff0000, v243
	v_fmac_f32_e32 v248, v186, v244
	v_fmac_f32_e32 v249, v187, v245
	v_fmac_f32_e32 v250, v188, v246
	v_fmac_f32_e32 v251, v189, v247
	v_mul_f32_e32 v244, 0xbfb8aa3b, v248
	v_mul_f32_e32 v245, 0xbfb8aa3b, v249
	v_mul_f32_e32 v246, 0xbfb8aa3b, v250
	v_mul_f32_e32 v247, 0xbfb8aa3b, v251
	v_exp_f32_e32 v244, v244
	v_exp_f32_e32 v245, v245
	v_exp_f32_e32 v246, v246
	v_exp_f32_e32 v247, v247
	v_add_f32_e32 v244, 1.0, v244
	v_add_f32_e32 v245, 1.0, v245
	v_add_f32_e32 v246, 1.0, v246
	v_add_f32_e32 v247, 1.0, v247
	v_rcp_f32_e32 v244, v244
	v_rcp_f32_e32 v245, v245
	v_rcp_f32_e32 v246, v246
	v_rcp_f32_e32 v247, v247
	v_mul_f32_e32 v248, v248, v244
	v_mul_f32_e32 v249, v249, v245
	v_mul_f32_e32 v250, v250, v246
	v_mul_f32_e32 v251, v251, v247
	v_mul_f32_e32 v18, v18, v248
	v_mul_f32_e32 v19, v19, v249
	v_mul_f32_e32 v20, v20, v250
	v_mul_f32_e32 v21, v21, v251
	v_cvt_pk_bf16_f32 v18, v18, v19
	v_cvt_pk_bf16_f32 v19, v20, v21
	ds_read_b64 v[238:239], v199 offset:24576
	ds_read_b64 v[240:241], v201 offset:24576
	ds_read_b64 v[242:243], v205
	s_waitcnt lgkmcnt(3)
	v_lshlrev_b32_e32 v244, 16, v232
	v_and_b32_e32 v245, 0xffff0000, v232
	v_lshlrev_b32_e32 v246, 16, v233
	v_and_b32_e32 v247, 0xffff0000, v233
	v_mul_f32_e32 v248, v142, v244
	v_mul_f32_e32 v249, v143, v245
	v_mul_f32_e32 v250, v144, v246
	v_mul_f32_e32 v251, v145, v247
	v_lshlrev_b32_e32 v244, 16, v234
	v_and_b32_e32 v245, 0xffff0000, v234
	v_lshlrev_b32_e32 v246, 16, v235
	v_and_b32_e32 v247, 0xffff0000, v235
	v_fmac_f32_e32 v248, v146, v244
	v_fmac_f32_e32 v249, v147, v245
	v_fmac_f32_e32 v250, v148, v246
	v_fmac_f32_e32 v251, v149, v247
	v_lshlrev_b32_e32 v244, 16, v236
	v_and_b32_e32 v245, 0xffff0000, v236
	v_lshlrev_b32_e32 v246, 16, v237
	v_and_b32_e32 v247, 0xffff0000, v237
	v_fmac_f32_e32 v248, v150, v244
	v_fmac_f32_e32 v249, v151, v245
	v_fmac_f32_e32 v250, v152, v246
	v_fmac_f32_e32 v251, v153, v247
	v_mul_f32_e32 v244, 0xbfb8aa3b, v248
	v_mul_f32_e32 v245, 0xbfb8aa3b, v249
	v_mul_f32_e32 v246, 0xbfb8aa3b, v250
	v_mul_f32_e32 v247, 0xbfb8aa3b, v251
	v_exp_f32_e32 v244, v244
	v_exp_f32_e32 v245, v245
	v_exp_f32_e32 v246, v246
	v_exp_f32_e32 v247, v247
	v_add_f32_e32 v244, 1.0, v244
	v_add_f32_e32 v245, 1.0, v245
	v_add_f32_e32 v246, 1.0, v246
	v_add_f32_e32 v247, 1.0, v247
	v_rcp_f32_e32 v244, v244
	v_rcp_f32_e32 v245, v245
	v_rcp_f32_e32 v246, v246
	v_rcp_f32_e32 v247, v247
	v_mul_f32_e32 v248, v248, v244
	v_mul_f32_e32 v249, v249, v245
	v_mul_f32_e32 v250, v250, v246
	v_mul_f32_e32 v251, v251, v247
	v_mul_f32_e32 v14, v14, v248
	v_mul_f32_e32 v15, v15, v249
	v_mul_f32_e32 v16, v16, v250
	v_mul_f32_e32 v17, v17, v251
	v_cvt_pk_bf16_f32 v14, v14, v15
	v_cvt_pk_bf16_f32 v15, v16, v17
	ds_read_b64 v[232:233], v198 offset:24832
	ds_read_b64 v[234:235], v200 offset:24832
	ds_read_b64 v[236:237], v204 offset:256
	s_waitcnt lgkmcnt(3)
	v_lshlrev_b32_e32 v244, 16, v238
	v_and_b32_e32 v245, 0xffff0000, v238
	v_lshlrev_b32_e32 v246, 16, v239
	v_and_b32_e32 v247, 0xffff0000, v239
	v_mul_f32_e32 v248, v154, v244
	v_mul_f32_e32 v249, v155, v245
	v_mul_f32_e32 v250, v156, v246
	v_mul_f32_e32 v251, v157, v247
	v_lshlrev_b32_e32 v244, 16, v240
	v_and_b32_e32 v245, 0xffff0000, v240
	v_lshlrev_b32_e32 v246, 16, v241
	v_and_b32_e32 v247, 0xffff0000, v241
	v_fmac_f32_e32 v248, v158, v244
	v_fmac_f32_e32 v249, v159, v245
	v_fmac_f32_e32 v250, v160, v246
	v_fmac_f32_e32 v251, v161, v247
	v_lshlrev_b32_e32 v244, 16, v242
	v_and_b32_e32 v245, 0xffff0000, v242
	v_lshlrev_b32_e32 v246, 16, v243
	v_and_b32_e32 v247, 0xffff0000, v243
	v_fmac_f32_e32 v248, v162, v244
	v_fmac_f32_e32 v249, v163, v245
	v_fmac_f32_e32 v250, v164, v246
	v_fmac_f32_e32 v251, v165, v247
	v_mul_f32_e32 v244, 0xbfb8aa3b, v248
	v_mul_f32_e32 v245, 0xbfb8aa3b, v249
	v_mul_f32_e32 v246, 0xbfb8aa3b, v250
	v_mul_f32_e32 v247, 0xbfb8aa3b, v251
	v_exp_f32_e32 v244, v244
	v_exp_f32_e32 v245, v245
	v_exp_f32_e32 v246, v246
	v_exp_f32_e32 v247, v247
	v_add_f32_e32 v244, 1.0, v244
	v_add_f32_e32 v245, 1.0, v245
	v_add_f32_e32 v246, 1.0, v246
	v_add_f32_e32 v247, 1.0, v247
	v_rcp_f32_e32 v244, v244
	v_rcp_f32_e32 v245, v245
	v_rcp_f32_e32 v246, v246
	v_rcp_f32_e32 v247, v247
	v_mul_f32_e32 v248, v248, v244
	v_mul_f32_e32 v249, v249, v245
	v_mul_f32_e32 v250, v250, v246
	v_mul_f32_e32 v251, v251, v247
	v_mul_f32_e32 v10, v10, v248
	v_mul_f32_e32 v11, v11, v249
	v_mul_f32_e32 v12, v12, v250
	v_mul_f32_e32 v13, v13, v251
	v_cvt_pk_bf16_f32 v10, v10, v11
	v_cvt_pk_bf16_f32 v11, v12, v13
	ds_read_b64 v[238:239], v199 offset:24832
	ds_read_b64 v[240:241], v201 offset:24832
	ds_read_b64 v[242:243], v205 offset:256
	s_waitcnt lgkmcnt(3)
	v_lshlrev_b32_e32 v244, 16, v232
	v_and_b32_e32 v245, 0xffff0000, v232
	v_lshlrev_b32_e32 v246, 16, v233
	v_and_b32_e32 v247, 0xffff0000, v233
	v_mul_f32_e32 v248, v166, v244
	v_mul_f32_e32 v249, v167, v245
	v_mul_f32_e32 v250, v168, v246
	v_mul_f32_e32 v251, v169, v247
	v_lshlrev_b32_e32 v244, 16, v234
	v_and_b32_e32 v245, 0xffff0000, v234
	v_lshlrev_b32_e32 v246, 16, v235
	v_and_b32_e32 v247, 0xffff0000, v235
	v_fmac_f32_e32 v248, v170, v244
	v_fmac_f32_e32 v249, v171, v245
	v_fmac_f32_e32 v250, v172, v246
	v_fmac_f32_e32 v251, v173, v247
	v_lshlrev_b32_e32 v244, 16, v236
	v_and_b32_e32 v245, 0xffff0000, v236
	v_lshlrev_b32_e32 v246, 16, v237
	v_and_b32_e32 v247, 0xffff0000, v237
	v_fmac_f32_e32 v248, v174, v244
	v_fmac_f32_e32 v249, v175, v245
	v_fmac_f32_e32 v250, v176, v246
	v_fmac_f32_e32 v251, v177, v247
	v_mul_f32_e32 v244, 0xbfb8aa3b, v248
	v_mul_f32_e32 v245, 0xbfb8aa3b, v249
	v_mul_f32_e32 v246, 0xbfb8aa3b, v250
	v_mul_f32_e32 v247, 0xbfb8aa3b, v251
	v_exp_f32_e32 v244, v244
	v_exp_f32_e32 v245, v245
	v_exp_f32_e32 v246, v246
	v_exp_f32_e32 v247, v247
	v_add_f32_e32 v244, 1.0, v244
	v_add_f32_e32 v245, 1.0, v245
	v_add_f32_e32 v246, 1.0, v246
	v_add_f32_e32 v247, 1.0, v247
	v_rcp_f32_e32 v244, v244
	v_rcp_f32_e32 v245, v245
	v_rcp_f32_e32 v246, v246
	v_rcp_f32_e32 v247, v247
	v_mul_f32_e32 v248, v248, v244
	v_mul_f32_e32 v249, v249, v245
	v_mul_f32_e32 v250, v250, v246
	v_mul_f32_e32 v251, v251, v247
	v_mul_f32_e32 v6, v6, v248
	v_mul_f32_e32 v7, v7, v249
	v_mul_f32_e32 v8, v8, v250
	v_mul_f32_e32 v9, v9, v251
	v_cvt_pk_bf16_f32 v6, v6, v7
	v_cvt_pk_bf16_f32 v7, v8, v9
	s_waitcnt lgkmcnt(0)
	v_lshlrev_b32_e32 v244, 16, v238
	v_and_b32_e32 v245, 0xffff0000, v238
	v_lshlrev_b32_e32 v246, 16, v239
	v_and_b32_e32 v247, 0xffff0000, v239
	v_mul_f32_e32 v248, v178, v244
	v_mul_f32_e32 v249, v179, v245
	v_mul_f32_e32 v250, v180, v246
	v_mul_f32_e32 v251, v181, v247
	v_lshlrev_b32_e32 v244, 16, v240
	v_and_b32_e32 v245, 0xffff0000, v240
	v_lshlrev_b32_e32 v246, 16, v241
	v_and_b32_e32 v247, 0xffff0000, v241
	v_fmac_f32_e32 v248, v182, v244
	v_fmac_f32_e32 v249, v183, v245
	v_fmac_f32_e32 v250, v184, v246
	v_fmac_f32_e32 v251, v185, v247
	v_lshlrev_b32_e32 v244, 16, v242
	v_and_b32_e32 v245, 0xffff0000, v242
	v_lshlrev_b32_e32 v246, 16, v243
	v_and_b32_e32 v247, 0xffff0000, v243
	v_fmac_f32_e32 v248, v186, v244
	v_fmac_f32_e32 v249, v187, v245
	v_fmac_f32_e32 v250, v188, v246
	v_fmac_f32_e32 v251, v189, v247
	v_mul_f32_e32 v244, 0xbfb8aa3b, v248
	v_mul_f32_e32 v245, 0xbfb8aa3b, v249
	v_mul_f32_e32 v246, 0xbfb8aa3b, v250
	v_mul_f32_e32 v247, 0xbfb8aa3b, v251
	v_exp_f32_e32 v244, v244
	v_exp_f32_e32 v245, v245
	v_exp_f32_e32 v246, v246
	v_exp_f32_e32 v247, v247
	v_add_f32_e32 v244, 1.0, v244
	v_add_f32_e32 v245, 1.0, v245
	v_add_f32_e32 v246, 1.0, v246
	v_add_f32_e32 v247, 1.0, v247
	v_rcp_f32_e32 v244, v244
	v_rcp_f32_e32 v245, v245
	v_rcp_f32_e32 v246, v246
	v_rcp_f32_e32 v247, v247
	v_mul_f32_e32 v248, v248, v244
	v_mul_f32_e32 v249, v249, v245
	v_mul_f32_e32 v250, v250, v246
	v_mul_f32_e32 v251, v251, v247
	v_mul_f32_e32 v2, v2, v248
	v_mul_f32_e32 v3, v3, v249
	v_mul_f32_e32 v4, v4, v250
	v_mul_f32_e32 v5, v5, v251
	v_cvt_pk_bf16_f32 v2, v2, v3
	v_cvt_pk_bf16_f32 v3, v4, v5
	v_lshrrev_b32_e32 v132, 1, v129
	v_lshl_add_u32 v132, v130, 2, v132
	v_and_b32_e32 v133, 1, v129
	v_lshlrev_b32_e32 v133, 3, v133
	v_lshl_add_u32 v134, v131, 6, v128
	v_lshlrev_b32_e32 v135, 9, v134
	v_add_u32_e32 v135, v135, v133
	v_mov_b32_e32 v136, v132
	v_xor_b32_e32 v136, v136, v128
	v_lshl_add_u32 v190, v136, 4, v135
	v_add_u32_e32 v192, 0x10000, v190
	v_add_u32_e32 v136, 2, v132
	v_xor_b32_e32 v136, v136, v128
	v_lshl_add_u32 v191, v136, 4, v135
	v_add_u32_e32 v193, 0x10000, v191
	s_waitcnt lgkmcnt(0)
	s_barrier
	ds_write_b64 v190, v[138:139]
	ds_write_b64 v191, v[122:123]
	ds_write_b64 v190, v[118:119] offset:256
	ds_write_b64 v191, v[114:115] offset:256
	ds_write_b64 v190, v[110:111] offset:8192
	ds_write_b64 v191, v[106:107] offset:8192
	ds_write_b64 v190, v[102:103] offset:8448
	ds_write_b64 v191, v[98:99] offset:8448
	ds_write_b64 v190, v[94:95] offset:16384
	ds_write_b64 v191, v[90:91] offset:16384
	ds_write_b64 v190, v[86:87] offset:16640
	ds_write_b64 v191, v[82:83] offset:16640
	ds_write_b64 v190, v[78:79] offset:24576
	ds_write_b64 v191, v[74:75] offset:24576
	ds_write_b64 v190, v[70:71] offset:24832
	ds_write_b64 v191, v[66:67] offset:24832
	ds_write_b64 v192, v[62:63]
	ds_write_b64 v193, v[58:59]
	ds_write_b64 v192, v[54:55] offset:256
	ds_write_b64 v193, v[50:51] offset:256
	ds_write_b64 v192, v[46:47] offset:8192
	ds_write_b64 v193, v[42:43] offset:8192
	ds_write_b64 v192, v[38:39] offset:8448
	ds_write_b64 v193, v[34:35] offset:8448
	ds_write_b64 v192, v[30:31] offset:16384
	ds_write_b64 v193, v[26:27] offset:16384
	ds_write_b64 v192, v[22:23] offset:16640
	ds_write_b64 v193, v[18:19] offset:16640
	ds_write_b64 v192, v[14:15] offset:24576
	ds_write_b64 v193, v[10:11] offset:24576
	ds_write_b64 v192, v[6:7] offset:24832
	ds_write_b64 v193, v[2:3] offset:24832
	v_lshlrev_b32_e32 v194, 4, v126
	v_lshl_add_u32 v194, v127, 10, v194
	v_add_u32_e32 v195, 0x10000, v194
	v_lshrrev_b32_e32 v132, 5, v126
	v_lshl_add_u32 v133, v127, 1, v132
	v_and_b32_e32 v134, 31, v126
	v_xor_b32_e32 v134, v134, v133
	v_mul_u32_u24_e32 v196, 0x2c00, v133
	v_lshl_add_u32 v196, v134, 4, v196
	s_waitcnt lgkmcnt(0)
	s_barrier
	ds_read_b128 v[142:145], v194
	ds_read_b128 v[146:149], v194 offset:8192
	ds_read_b128 v[150:153], v194 offset:16384
	ds_read_b128 v[154:157], v194 offset:24576
	ds_read_b128 v[158:161], v194 offset:32768
	ds_read_b128 v[162:165], v194 offset:40960
	ds_read_b128 v[166:169], v194 offset:49152
	ds_read_b128 v[170:173], v194 offset:57344
	s_waitcnt lgkmcnt(7)
	global_store_dwordx4 v196, v[142:145], s[14:15]
	s_add_u32 s14, s14, 0x2c000
	s_addc_u32 s15, s15, 0
	s_nop 0
	ds_read_b128 v[142:145], v195
	s_waitcnt lgkmcnt(7)
	global_store_dwordx4 v196, v[146:149], s[14:15]
	s_add_u32 s14, s14, 0x2c000
	s_addc_u32 s15, s15, 0
	s_nop 0
	ds_read_b128 v[146:149], v195 offset:8192
	s_waitcnt lgkmcnt(7)
	global_store_dwordx4 v196, v[150:153], s[14:15]
	s_add_u32 s14, s14, 0x2c000
	s_addc_u32 s15, s15, 0
	s_nop 0
	ds_read_b128 v[150:153], v195 offset:16384
	s_waitcnt lgkmcnt(7)
	global_store_dwordx4 v196, v[154:157], s[14:15]
	s_add_u32 s14, s14, 0x2c000
	s_addc_u32 s15, s15, 0
	s_nop 0
	ds_read_b128 v[154:157], v195 offset:24576
	s_waitcnt lgkmcnt(7)
	global_store_dwordx4 v196, v[158:161], s[14:15]
	s_add_u32 s14, s14, 0x2c000
	s_addc_u32 s15, s15, 0
	s_nop 0
	ds_read_b128 v[158:161], v195 offset:32768
	s_waitcnt lgkmcnt(7)
	global_store_dwordx4 v196, v[162:165], s[14:15]
	s_add_u32 s14, s14, 0x2c000
	s_addc_u32 s15, s15, 0
	s_nop 0
	ds_read_b128 v[162:165], v195 offset:40960
	s_waitcnt lgkmcnt(7)
	global_store_dwordx4 v196, v[166:169], s[14:15]
	s_add_u32 s14, s14, 0x2c000
	s_addc_u32 s15, s15, 0
	s_nop 0
	ds_read_b128 v[166:169], v195 offset:49152
	s_waitcnt lgkmcnt(7)
	global_store_dwordx4 v196, v[170:173], s[14:15]
	s_add_u32 s14, s14, 0x2c000
	s_addc_u32 s15, s15, 0
	s_nop 0
	ds_read_b128 v[170:173], v195 offset:57344
	s_waitcnt lgkmcnt(7)
	global_store_dwordx4 v196, v[142:145], s[14:15]
	s_add_u32 s14, s14, 0x2c000
	s_addc_u32 s15, s15, 0
	s_waitcnt lgkmcnt(6)
	global_store_dwordx4 v196, v[146:149], s[14:15]
	s_add_u32 s14, s14, 0x2c000
	s_addc_u32 s15, s15, 0
	s_waitcnt lgkmcnt(5)
	global_store_dwordx4 v196, v[150:153], s[14:15]
	s_add_u32 s14, s14, 0x2c000
	s_addc_u32 s15, s15, 0
	s_waitcnt lgkmcnt(4)
	global_store_dwordx4 v196, v[154:157], s[14:15]
	s_add_u32 s14, s14, 0x2c000
	s_addc_u32 s15, s15, 0
	s_waitcnt lgkmcnt(3)
	global_store_dwordx4 v196, v[158:161], s[14:15]
	s_add_u32 s14, s14, 0x2c000
	s_addc_u32 s15, s15, 0
	s_waitcnt lgkmcnt(2)
	global_store_dwordx4 v196, v[162:165], s[14:15]
	s_add_u32 s14, s14, 0x2c000
	s_addc_u32 s15, s15, 0
	s_waitcnt lgkmcnt(1)
	global_store_dwordx4 v196, v[166:169], s[14:15]
	s_add_u32 s14, s14, 0x2c000
	s_addc_u32 s15, s15, 0
	s_waitcnt lgkmcnt(0)
	global_store_dwordx4 v196, v[170:173], s[14:15]
	v_readlane_b32 s36, v253, 33
	v_readlane_b32 s37, v253, 34
	v_readlane_b32 s38, v253, 35
	v_readlane_b32 s39, v253, 36
	v_readlane_b32 s40, v253, 37
	v_readlane_b32 s41, v253, 38
	v_readlane_b32 s42, v253, 39
	v_readlane_b32 s43, v253, 40
	v_readlane_b32 s44, v253, 41
	v_readlane_b32 s45, v253, 42
	v_readlane_b32 s46, v253, 43
	v_readlane_b32 s47, v253, 44
	v_readlane_b32 s48, v253, 45
	v_readlane_b32 s49, v253, 46
	v_readlane_b32 s50, v253, 47
	v_readlane_b32 s51, v253, 48
	s_add_i32 s76, s76, s96
	s_cmpk_gt_i32 s76, 0x3ff
	s_cbranch_scc1 .LBB0_69
	s_branch .LBB0_31
